# in-proj K loops unrolled by the 3 ring slots: per-slot fragment-read addresses formed once per tile, six vector adds per K block removed
# speedup vs baseline: 1.0043x; 1.0043x over previous
; DI int otid() { int t = threadIdx.x; asm volatile("" : "+v"(t)); return t; }
; #define G_ISSUE(ks_, buf_) do { \
;     const bf16_t* wq_ = wp + (ks_) * wks; const bf16_t* xq_ = xp + (ks_) * xks; char* lb_ = ld + (buf_) * STAGE; \
;     dma16(wq_, lb_); dma16(wq_ + 2048, lb_ + 4096); \
;     _Pragma("unroll") for (int i_ = 0; i_ < TJ; ++i_) dma16(xq_ + i_ * 2048, lb_ + 8192 + i_ * 4096); } while (0)
; template <bool VMODE, int TJ>
; DI void gemm_mainloop(const bf16_t* __restrict__ W, const bf16_t* __restrict__ X, int NW, char* smem, f32x16 (&acc)[2][TJ]) {
;     constexpr int XROWS = 64 * TJ, STAGE = (128 + XROWS) * 64, NPW = 2 + TJ;
;     const int tid = otid(), lane = tid & 63, wave = tid >> 6, r = lane & 31, h = lane >> 5, wf = wave & 1, wt = wave >> 1;
;     const int goff = (16 * wave + (lane >> 2)) * 32 + (((lane & 3) ^ (lane >> 4)) << 3);
;     const bf16_t* wp = W + goff;
;     const bf16_t* xp = X + goff;
;     const size_t wks = (size_t)NW * 32, xks = (size_t)NTOK * 32;
;     char* ld = smem + tid * 16;
;     ...
;     const int xr = (r >> 2) & 3;
;     const int fo0 = r * 64 + (((0 + h) ^ xr) << 4), fo1 = r * 64 + (((2 + h) ^ xr) << 4);
;     __syncthreads();
;     ...
;         G_ISSUE(0, 0);
;         G_ISSUE(1, 1);
;         int bc = 0, bn = 2;
.LBB0_200:
	s_load_dwordx2 s[4:5], s[0:1], 0xd0
	s_load_dwordx2 s[6:7], s[0:1], 0xb8
	s_mul_hi_i32 s47, s50, 0x38e38e39
	s_waitcnt lgkmcnt(0)
	s_add_u32 s8, s4, s63
	s_addc_u32 s9, s5, s62
	s_ashr_i32 s59, s58, 31
	s_lshl_b64 s[4:5], s[58:59], 6
	s_add_u32 s52, s8, s4
	s_addc_u32 s53, s9, s5
	s_ashr_i32 s51, s50, 31
	s_lshl_b64 s[4:5], s[50:51], 14
	s_add_u32 s56, s6, s4
	s_addc_u32 s57, s7, s5
	s_mov_b64 s[4:5], -1
	s_cmp_lt_i32 s46, 0
	s_cbranch_scc0 .LBB0_287
	v_mov_b32_e32 v4, v200
	s_movk_i32 s4, 0xffe0
	v_bfe_u32 v1, v4, 4, 2
	v_bitop3_b32 v1, v1, v4, 3 bitop3:0x78
	v_lshlrev_b32_e32 v0, 3, v4
	v_lshlrev_b32_e32 v1, 3, v1
	v_and_or_b32 v0, v0, s4, v1
	v_bfe_u32 v5, v4, 5, 1
	v_ashrrev_i32_e32 v1, 31, v0
	v_lshl_add_u32 v130, v4, 4, 32
	v_bfe_u32 v7, v4, 2, 2
	v_lshlrev_b64 v[128:129], 1, v[0:1]
	v_bitop3_b32 v9, v5, v7, 2 bitop3:0x36
	v_readfirstlane_b32 s4, v130
	v_add_u32_e32 v7, 0x1000, v130
	v_lshl_add_u64 v[0:1], s[52:53], 0, v[128:129]
	v_lshrrev_b32_e32 v6, 2, v4
	s_mov_b32 m0, s4
	v_readfirstlane_b32 s4, v7
	v_lshlrev_b32_e32 v8, 6, v4
	v_bitop3_b32 v6, v5, v6, 3 bitop3:0x78
	s_barrier
	global_load_lds_dwordx4 v[0:1], off
	v_lshl_add_u64 v[4:5], v[0:1], 0, s[26:27]
	s_mov_b32 m0, s4
	v_add_u32_e32 v7, 0x3000, v130
	global_load_lds_dwordx4 v[4:5], off
	v_add_u32_e32 v4, 0x2000, v130
	v_lshl_add_u64 v[2:3], s[56:57], 0, v[128:129]
	v_readfirstlane_b32 s4, v4
	s_mov_b32 m0, s4
	v_readfirstlane_b32 s4, v7
	v_add_u32_e32 v7, 0x4000, v130
	global_load_lds_dwordx4 v[2:3], off
	v_lshl_add_u64 v[4:5], v[2:3], 0, s[26:27]
	s_mov_b32 m0, s4
	v_readfirstlane_b32 s4, v7
	v_add_u32_e32 v7, 0x5000, v130
	global_load_lds_dwordx4 v[4:5], off
	v_lshl_add_u64 v[4:5], v[2:3], 0, s[16:17]
	s_mov_b32 m0, s4
	v_readfirstlane_b32 s4, v7
	global_load_lds_dwordx4 v[4:5], off
	v_lshl_add_u64 v[4:5], v[2:3], 0, s[90:91]
	s_mov_b32 m0, s4
	s_mov_b64 s[4:5], 0x38000
	global_load_lds_dwordx4 v[4:5], off
	v_and_b32_e32 v10, 0x7c0, v8
	v_lshl_add_u64 v[4:5], v[0:1], 0, s[4:5]
	s_mov_b64 s[4:5], 0x120000
	v_add_u32_e32 v11, 0x6000, v130
	v_lshl_or_b32 v131, v6, 4, v10
	v_lshl_add_u64 v[6:7], v[2:3], 0, s[4:5]
	v_readfirstlane_b32 s4, v11
	s_mov_b32 m0, s4
	s_mov_b64 s[4:5], 0x39000
	global_load_lds_dwordx4 v[4:5], off
	v_add_u32_e32 v4, 0x7000, v130
	v_lshl_add_u64 v[0:1], v[0:1], 0, s[4:5]
	v_readfirstlane_b32 s4, v4
	s_mov_b32 m0, s4
	v_add_u32_e32 v4, 0x9000, v130
	global_load_lds_dwordx4 v[0:1], off
	v_add_u32_e32 v0, 0x8000, v130
	s_mov_b32 s8, 2
	v_readfirstlane_b32 s4, v0
	s_mov_b32 m0, s4
	s_mov_b64 s[4:5], 0x121000
	v_lshl_add_u64 v[0:1], v[2:3], 0, s[4:5]
	v_readfirstlane_b32 s4, v4
	global_load_lds_dwordx4 v[6:7], off
	s_mov_b32 m0, s4
	s_mov_b64 s[4:5], 0x122000
	v_add_u32_e32 v4, 0xa000, v130
	global_load_lds_dwordx4 v[0:1], off
	v_lshl_add_u64 v[0:1], v[2:3], 0, s[4:5]
	v_readfirstlane_b32 s4, v4
	s_mov_b32 m0, s4
	s_mov_b64 s[4:5], 0x123000
	global_load_lds_dwordx4 v[0:1], off
	v_lshl_add_u64 v[0:1], v[2:3], 0, s[4:5]
	v_add_u32_e32 v2, 0xb000, v130
	v_lshl_or_b32 v132, v9, 4, v10
	v_readfirstlane_b32 s4, v2
	s_mov_b32 m0, s4
	v_and_b32_e32 v134, 0x1000, v8
	global_load_lds_dwordx4 v[0:1], off
	v_mov_b32_e32 v0, 0
	v_and_b32_e32 v133, 0xffffe000, v8
	s_mov_b32 s28, 0
	s_mov_b32 s9, 30
	s_mov_b64 s[4:5], s[52:53]
	s_mov_b64 s[6:7], s[56:57]
	v_mov_b32_e32 v1, v0
	v_mov_b32_e32 v2, v0
	v_mov_b32_e32 v3, v0
	v_mov_b32_e32 v4, v0
	v_mov_b32_e32 v5, v0
	v_mov_b32_e32 v6, v0
	v_mov_b32_e32 v7, v0
	v_mov_b32_e32 v8, v0
	v_mov_b32_e32 v9, v0
	v_mov_b32_e32 v10, v0
	v_mov_b32_e32 v11, v0
	v_mov_b32_e32 v12, v0
	v_mov_b32_e32 v13, v0
	v_mov_b32_e32 v14, v0
	v_mov_b32_e32 v15, v0
	v_mov_b32_e32 v32, v0
	v_mov_b32_e32 v33, v0
	v_mov_b32_e32 v34, v0
	v_mov_b32_e32 v35, v0
	v_mov_b32_e32 v36, v0
	v_mov_b32_e32 v37, v0
	v_mov_b32_e32 v38, v0
	v_mov_b32_e32 v39, v0
	v_mov_b32_e32 v40, v0
	v_mov_b32_e32 v41, v0
	v_mov_b32_e32 v42, v0
	v_mov_b32_e32 v43, v0
	v_mov_b32_e32 v44, v0
	v_mov_b32_e32 v45, v0
	v_mov_b32_e32 v46, v0
	v_mov_b32_e32 v47, v0
	v_mov_b32_e32 v64, v0
	v_mov_b32_e32 v65, v0
	v_mov_b32_e32 v66, v0
	v_mov_b32_e32 v67, v0
	v_mov_b32_e32 v68, v0
	v_mov_b32_e32 v69, v0
	v_mov_b32_e32 v70, v0
	v_mov_b32_e32 v71, v0
	v_mov_b32_e32 v72, v0
	v_mov_b32_e32 v73, v0
	v_mov_b32_e32 v74, v0
	v_mov_b32_e32 v75, v0
	v_mov_b32_e32 v76, v0
	v_mov_b32_e32 v77, v0
	v_mov_b32_e32 v78, v0
	v_mov_b32_e32 v79, v0
	v_mov_b32_e32 v96, v0
	v_mov_b32_e32 v97, v0
	v_mov_b32_e32 v98, v0
	v_mov_b32_e32 v99, v0
	v_mov_b32_e32 v100, v0
	v_mov_b32_e32 v101, v0
	v_mov_b32_e32 v102, v0
	v_mov_b32_e32 v103, v0
	v_mov_b32_e32 v104, v0
	v_mov_b32_e32 v105, v0
	v_mov_b32_e32 v106, v0
	v_mov_b32_e32 v107, v0
	v_mov_b32_e32 v108, v0
	v_mov_b32_e32 v109, v0
	v_mov_b32_e32 v110, v0
	v_mov_b32_e32 v111, v0
	v_mov_b32_e32 v16, v0
	v_mov_b32_e32 v17, v0
	v_mov_b32_e32 v18, v0
	v_mov_b32_e32 v19, v0
	v_mov_b32_e32 v20, v0
	v_mov_b32_e32 v21, v0
	v_mov_b32_e32 v22, v0
	v_mov_b32_e32 v23, v0
	v_mov_b32_e32 v24, v0
	v_mov_b32_e32 v25, v0
	v_mov_b32_e32 v26, v0
	v_mov_b32_e32 v27, v0
	v_mov_b32_e32 v28, v0
	v_mov_b32_e32 v29, v0
	v_mov_b32_e32 v30, v0
	v_mov_b32_e32 v31, v0
	v_mov_b32_e32 v48, v0
	v_mov_b32_e32 v49, v0
	v_mov_b32_e32 v50, v0
	v_mov_b32_e32 v51, v0
	v_mov_b32_e32 v52, v0
	v_mov_b32_e32 v53, v0
	v_mov_b32_e32 v54, v0
	v_mov_b32_e32 v55, v0
	v_mov_b32_e32 v56, v0
	v_mov_b32_e32 v57, v0
	v_mov_b32_e32 v58, v0
	v_mov_b32_e32 v59, v0
	v_mov_b32_e32 v60, v0
	v_mov_b32_e32 v61, v0
	v_mov_b32_e32 v62, v0
	v_mov_b32_e32 v63, v0
	v_mov_b32_e32 v80, v0
	v_mov_b32_e32 v81, v0
	v_mov_b32_e32 v82, v0
	v_mov_b32_e32 v83, v0
	v_mov_b32_e32 v84, v0
	v_mov_b32_e32 v85, v0
	v_mov_b32_e32 v86, v0
; #define MFMA(a, b, c) __builtin_amdgcn_mfma_f32_32x32x16_bf16((a), (b), (c), 0, 0, 0)
; #define G_ISSUE(ks_, buf_) do { \
;     const bf16_t* wq_ = wp + (ks_) * wks; const bf16_t* xq_ = xp + (ks_) * xks; char* lb_ = ld + (buf_) * STAGE; \
;     dma16(wq_, lb_); dma16(wq_ + 2048, lb_ + 4096); \
;     _Pragma("unroll") for (int i_ = 0; i_ < TJ; ++i_) dma16(xq_ + i_ * 2048, lb_ + 8192 + i_ * 4096); } while (0)
; template <bool VMODE, int TJ>
; DI void gemm_mainloop(const bf16_t* __restrict__ W, const bf16_t* __restrict__ X, int NW, char* smem, f32x16 (&acc)[2][TJ]) {
;     ...
;         for (int ks = 0; ks < 32; ++ks) {
;             if (ks < 31) asm volatile("s_waitcnt vmcnt(6)" ::: "memory");
;             else asm volatile("s_waitcnt vmcnt(0)" ::: "memory");
;             __builtin_amdgcn_s_barrier();
;             const char* sw = smem + bc * STAGE + wf * 64 * 64;
;             const char* sx = smem + bc * STAGE + 8192 + wt * (32 * TJ) * 64;
;             bf16x8 fw[2], fx[TJ], gw[2], gx[TJ];
; #pragma unroll
;             for (int i = 0; i < 2; ++i) fw[i] = *(const bf16x8*)(sw + i * 32 * 64 + fo0);
; #pragma unroll
;             for (int j = 0; j < TJ; ++j) fx[j] = *(const bf16x8*)(sx + j * 32 * 64 + fo0);
;             __builtin_amdgcn_sched_barrier(0);
;             if (ks + 2 < 32) G_ISSUE(ks + 2, bn);
;             __builtin_amdgcn_sched_barrier(0);
; #pragma unroll
;             for (int i = 0; i < 2; ++i) gw[i] = *(const bf16x8*)(sw + i * 32 * 64 + fo1);
; #pragma unroll
;             for (int j = 0; j < TJ; ++j) gx[j] = *(const bf16x8*)(sx + j * 32 * 64 + fo1);
; #pragma unroll
;             for (int i = 0; i < 2; ++i)
; #pragma unroll
;                 for (int j = 0; j < TJ; ++j) acc[i][j] = VMODE ? MFMA(fx[j], fw[i], acc[i][j]) : MFMA(fw[i], fx[j], acc[i][j]);
; #pragma unroll
;             for (int i = 0; i < 2; ++i)
; #pragma unroll
;                 for (int j = 0; j < TJ; ++j) acc[i][j] = VMODE ? MFMA(gx[j], gw[i], acc[i][j]) : MFMA(gw[i], gx[j], acc[i][j]);
	v_mov_b32_e32 v87, v0
	v_mov_b32_e32 v88, v0
	v_mov_b32_e32 v89, v0
	v_mov_b32_e32 v90, v0
	v_mov_b32_e32 v91, v0
	v_mov_b32_e32 v92, v0
	v_mov_b32_e32 v93, v0
	v_mov_b32_e32 v94, v0
	v_mov_b32_e32 v95, v0
	v_mov_b32_e32 v112, v0
	v_mov_b32_e32 v113, v0
	v_mov_b32_e32 v114, v0
	v_mov_b32_e32 v115, v0
	v_mov_b32_e32 v116, v0
	v_mov_b32_e32 v117, v0
	v_mov_b32_e32 v118, v0
	v_mov_b32_e32 v119, v0
	v_mov_b32_e32 v120, v0
	v_mov_b32_e32 v121, v0
	v_mov_b32_e32 v122, v0
	v_mov_b32_e32 v123, v0
	v_mov_b32_e32 v124, v0
	v_mov_b32_e32 v125, v0
	v_mov_b32_e32 v126, v0
	v_mov_b32_e32 v127, v0
	v_readfirstlane_b32 s100, v130
	v_add_u32_e32 v170, 0x38000, v128
	v_add_u32_e32 v171, 0x39000, v128
	v_add_u32_e32 v172, 0x120000, v128
	v_add_u32_e32 v173, 0x121000, v128
	v_add_u32_e32 v174, 0x122000, v128
	v_add_u32_e32 v175, 0x123000, v128
	v_add_u32_e32 v238, v134, v131
	v_add_u32_e32 v239, v133, v131
	v_add_u32_e32 v240, v134, v132
	v_add_u32_e32 v241, v133, v132
	v_add_u32_e32 v238, 0x20, v238
	v_add_u32_e32 v239, 0x20, v239
	v_add_u32_e32 v240, 0x20, v240
	v_add_u32_e32 v241, 0x20, v241
	v_add_u32_e32 v242, v134, v131
	v_add_u32_e32 v243, v133, v131
	v_add_u32_e32 v244, v134, v132
	v_add_u32_e32 v245, v133, v132
	v_add_u32_e32 v242, 0x6020, v242
	v_add_u32_e32 v243, 0x6020, v243
	v_add_u32_e32 v244, 0x6020, v244
	v_add_u32_e32 v245, 0x6020, v245
	v_add_u32_e32 v246, v134, v131
	v_add_u32_e32 v247, v133, v131
	v_add_u32_e32 v248, v134, v132
	v_add_u32_e32 v249, v133, v132
	v_add_u32_e32 v246, 0xc020, v246
	v_add_u32_e32 v247, 0xc020, v247
	v_add_u32_e32 v248, 0xc020, v248
	v_add_u32_e32 v249, 0xc020, v249
	s_mul_i32 s29, s28, 0x6000
	s_add_i32 s29, s29, 32
	v_add_u32_e32 v135, s29, v134
	v_add_u32_e32 v168, s29, v133
	v_add_u32_e32 v140, v135, v131
	v_add_u32_e32 v156, v168, v131
	s_waitcnt vmcnt(6)
	s_barrier
	ds_read_b128 v[136:139], v140
	ds_read_b128 v[140:143], v140 offset:2048
	ds_read_b128 v[144:147], v156 offset:8192
	ds_read_b128 v[148:151], v156 offset:10240
	ds_read_b128 v[152:155], v156 offset:12288
	ds_read_b128 v[156:159], v156 offset:14336
	s_mul_i32 s29, s8, 0x6000
	s_add_i32 s101, s29, s100
	s_add_i32 s29, s28, 1
	s_cmp_lg_u32 s28, 2
	s_cselect_b32 s28, s29, 0
	s_add_i32 s29, s8, 1
	s_cmp_lg_u32 s8, 2
	s_cselect_b32 s8, s29, 0
	s_add_i32 s9, s9, -1
	s_add_u32 s6, s6, 0x120000
	s_addc_u32 s7, s7, 0
	s_add_u32 s4, s4, 0x38000
	s_addc_u32 s5, s5, 0
	v_add_u32_e32 v169, v135, v132
	v_add_u32_e32 v192, v168, v132
	s_mov_b32 m0, s101
	s_waitcnt lgkmcnt(0)
	v_mfma_f32_32x32x16_bf16 v[112:127], v[136:139], v[144:147], v[112:127]
	global_load_lds_dwordx4 v170, s[4:5]
	s_add_u32 m0, s101, 0x1000
	ds_read_b128 v[160:163], v169
	v_mfma_f32_32x32x16_bf16 v[80:95], v[136:139], v[148:151], v[80:95]
	global_load_lds_dwordx4 v171, s[4:5]
	s_add_u32 m0, s101, 0x2000
	ds_read_b128 v[164:167], v192 offset:8192
	v_mfma_f32_32x32x16_bf16 v[48:63], v[136:139], v[152:155], v[48:63]
	global_load_lds_dwordx4 v172, s[6:7]
	s_add_u32 m0, s101, 0x3000
	ds_read_b128 v[176:179], v169 offset:2048
	v_mfma_f32_32x32x16_bf16 v[16:31], v[136:139], v[156:159], v[16:31]
	global_load_lds_dwordx4 v173, s[6:7]
	s_add_u32 m0, s101, 0x4000
	ds_read_b128 v[180:183], v192 offset:10240
	v_mfma_f32_32x32x16_bf16 v[96:111], v[140:143], v[144:147], v[96:111]
	global_load_lds_dwordx4 v174, s[6:7]
	s_add_u32 m0, s101, 0x5000
	ds_read_b128 v[184:187], v192 offset:12288
	v_mfma_f32_32x32x16_bf16 v[64:79], v[140:143], v[148:151], v[64:79]
	global_load_lds_dwordx4 v175, s[6:7]
	ds_read_b128 v[188:191], v192 offset:14336
	v_mfma_f32_32x32x16_bf16 v[32:47], v[140:143], v[152:155], v[32:47]
	v_mfma_f32_32x32x16_bf16 v[0:15], v[140:143], v[156:159], v[0:15]
.LBB0_202:
	s_waitcnt vmcnt(6)
	s_waitcnt lgkmcnt(0)
	s_barrier
	ds_read_b128 v[136:139], v242
	ds_read_b128 v[140:143], v242 offset:2048
	ds_read_b128 v[144:147], v243 offset:8192
	ds_read_b128 v[148:151], v243 offset:10240
	ds_read_b128 v[152:155], v243 offset:12288
	ds_read_b128 v[156:159], v243 offset:14336
	s_mul_i32 s29, s8, 0x6000
	s_add_i32 s101, s29, s100
	s_add_i32 s29, s28, 1
	s_cmp_lg_u32 s28, 2
	s_cselect_b32 s28, s29, 0
	s_add_i32 s29, s8, 1
	s_cmp_lg_u32 s8, 2
	s_cselect_b32 s8, s29, 0
	s_add_i32 s9, s9, -1
	s_add_u32 s6, s6, 0x120000
	s_addc_u32 s7, s7, 0
	s_add_u32 s4, s4, 0x38000
	s_addc_u32 s5, s5, 0
	s_mov_b32 m0, s101
	v_mfma_f32_32x32x16_bf16 v[112:127], v[160:163], v[164:167], v[112:127]
	global_load_lds_dwordx4 v170, s[4:5]
	s_add_u32 m0, s101, 0x1000
	v_mfma_f32_32x32x16_bf16 v[80:95], v[160:163], v[180:183], v[80:95]
	global_load_lds_dwordx4 v171, s[4:5]
	s_add_u32 m0, s101, 0x2000
	v_mfma_f32_32x32x16_bf16 v[48:63], v[160:163], v[184:187], v[48:63]
	global_load_lds_dwordx4 v172, s[6:7]
	s_add_u32 m0, s101, 0x3000
	v_mfma_f32_32x32x16_bf16 v[16:31], v[160:163], v[188:191], v[16:31]
	global_load_lds_dwordx4 v173, s[6:7]
	s_add_u32 m0, s101, 0x4000
	v_mfma_f32_32x32x16_bf16 v[96:111], v[176:179], v[164:167], v[96:111]
	global_load_lds_dwordx4 v174, s[6:7]
	s_add_u32 m0, s101, 0x5000
	v_mfma_f32_32x32x16_bf16 v[64:79], v[176:179], v[180:183], v[64:79]
	global_load_lds_dwordx4 v175, s[6:7]
	v_mfma_f32_32x32x16_bf16 v[32:47], v[176:179], v[184:187], v[32:47]
	v_mfma_f32_32x32x16_bf16 v[0:15], v[176:179], v[188:191], v[0:15]
	s_waitcnt lgkmcnt(0)
	v_mfma_f32_32x32x16_bf16 v[112:127], v[136:139], v[144:147], v[112:127]
	ds_read_b128 v[160:163], v244
	v_mfma_f32_32x32x16_bf16 v[80:95], v[136:139], v[148:151], v[80:95]
	ds_read_b128 v[164:167], v245 offset:8192
	v_mfma_f32_32x32x16_bf16 v[48:63], v[136:139], v[152:155], v[48:63]
	ds_read_b128 v[176:179], v244 offset:2048
	v_mfma_f32_32x32x16_bf16 v[16:31], v[136:139], v[156:159], v[16:31]
	ds_read_b128 v[180:183], v245 offset:10240
	v_mfma_f32_32x32x16_bf16 v[96:111], v[140:143], v[144:147], v[96:111]
	ds_read_b128 v[184:187], v245 offset:12288
	v_mfma_f32_32x32x16_bf16 v[64:79], v[140:143], v[148:151], v[64:79]
	ds_read_b128 v[188:191], v245 offset:14336
	v_mfma_f32_32x32x16_bf16 v[32:47], v[140:143], v[152:155], v[32:47]
	v_mfma_f32_32x32x16_bf16 v[0:15], v[140:143], v[156:159], v[0:15]
	s_cmp_lg_u32 s9, 0
	s_cbranch_scc0 .Lip3_exit_a
; #define MFMA(a, b, c) __builtin_amdgcn_mfma_f32_32x32x16_bf16((a), (b), (c), 0, 0, 0)
; #define G_ISSUE(ks_, buf_) do { \
;     const bf16_t* wq_ = wp + (ks_) * wks; const bf16_t* xq_ = xp + (ks_) * xks; char* lb_ = ld + (buf_) * STAGE; \
;     dma16(wq_, lb_); dma16(wq_ + 2048, lb_ + 4096); \
;     _Pragma("unroll") for (int i_ = 0; i_ < TJ; ++i_) dma16(xq_ + i_ * 2048, lb_ + 8192 + i_ * 4096); } while (0)
; template <bool VMODE, int TJ>
; DI void gemm_mainloop(const bf16_t* __restrict__ W, const bf16_t* __restrict__ X, int NW, char* smem, f32x16 (&acc)[2][TJ]) {
;     ...
;         for (int ks = 0; ks < 32; ++ks) {
;             if (ks < 31) asm volatile("s_waitcnt vmcnt(6)" ::: "memory");
;             else asm volatile("s_waitcnt vmcnt(0)" ::: "memory");
;             __builtin_amdgcn_s_barrier();
;             const char* sw = smem + bc * STAGE + wf * 64 * 64;
;             const char* sx = smem + bc * STAGE + 8192 + wt * (32 * TJ) * 64;
;             bf16x8 fw[2], fx[TJ], gw[2], gx[TJ];
; #pragma unroll
;             for (int i = 0; i < 2; ++i) fw[i] = *(const bf16x8*)(sw + i * 32 * 64 + fo0);
; #pragma unroll
;             for (int j = 0; j < TJ; ++j) fx[j] = *(const bf16x8*)(sx + j * 32 * 64 + fo0);
;             __builtin_amdgcn_sched_barrier(0);
;             if (ks + 2 < 32) G_ISSUE(ks + 2, bn);
;             __builtin_amdgcn_sched_barrier(0);
; #pragma unroll
;             for (int i = 0; i < 2; ++i) gw[i] = *(const bf16x8*)(sw + i * 32 * 64 + fo1);
; #pragma unroll
;             for (int j = 0; j < TJ; ++j) gx[j] = *(const bf16x8*)(sx + j * 32 * 64 + fo1);
; #pragma unroll
;             for (int i = 0; i < 2; ++i)
; #pragma unroll
;                 for (int j = 0; j < TJ; ++j) acc[i][j] = VMODE ? MFMA(fx[j], fw[i], acc[i][j]) : MFMA(fw[i], fx[j], acc[i][j]);
; #pragma unroll
;             for (int i = 0; i < 2; ++i)
; #pragma unroll
;                 for (int j = 0; j < TJ; ++j) acc[i][j] = VMODE ? MFMA(gx[j], gw[i], acc[i][j]) : MFMA(gw[i], gx[j], acc[i][j]);
;             bc = (bc == 2) ? 0 : bc + 1; bn = (bn == 2) ? 0 : bn + 1;
	s_waitcnt vmcnt(6)
	s_waitcnt lgkmcnt(0)
	s_barrier
	ds_read_b128 v[136:139], v246
	ds_read_b128 v[140:143], v246 offset:2048
	ds_read_b128 v[144:147], v247 offset:8192
	ds_read_b128 v[148:151], v247 offset:10240
	ds_read_b128 v[152:155], v247 offset:12288
	ds_read_b128 v[156:159], v247 offset:14336
	s_mul_i32 s29, s8, 0x6000
	s_add_i32 s101, s29, s100
	s_add_i32 s29, s28, 1
	s_cmp_lg_u32 s28, 2
	s_cselect_b32 s28, s29, 0
	s_add_i32 s29, s8, 1
	s_cmp_lg_u32 s8, 2
	s_cselect_b32 s8, s29, 0
	s_add_i32 s9, s9, -1
	s_add_u32 s6, s6, 0x120000
	s_addc_u32 s7, s7, 0
	s_add_u32 s4, s4, 0x38000
	s_addc_u32 s5, s5, 0
	s_mov_b32 m0, s101
	v_mfma_f32_32x32x16_bf16 v[112:127], v[160:163], v[164:167], v[112:127]
	global_load_lds_dwordx4 v170, s[4:5]
	s_add_u32 m0, s101, 0x1000
	v_mfma_f32_32x32x16_bf16 v[80:95], v[160:163], v[180:183], v[80:95]
	global_load_lds_dwordx4 v171, s[4:5]
	s_add_u32 m0, s101, 0x2000
	v_mfma_f32_32x32x16_bf16 v[48:63], v[160:163], v[184:187], v[48:63]
	global_load_lds_dwordx4 v172, s[6:7]
	s_add_u32 m0, s101, 0x3000
	v_mfma_f32_32x32x16_bf16 v[16:31], v[160:163], v[188:191], v[16:31]
	global_load_lds_dwordx4 v173, s[6:7]
	s_add_u32 m0, s101, 0x4000
	v_mfma_f32_32x32x16_bf16 v[96:111], v[176:179], v[164:167], v[96:111]
	global_load_lds_dwordx4 v174, s[6:7]
	s_add_u32 m0, s101, 0x5000
	v_mfma_f32_32x32x16_bf16 v[64:79], v[176:179], v[180:183], v[64:79]
	global_load_lds_dwordx4 v175, s[6:7]
	v_mfma_f32_32x32x16_bf16 v[32:47], v[176:179], v[184:187], v[32:47]
	v_mfma_f32_32x32x16_bf16 v[0:15], v[176:179], v[188:191], v[0:15]
	s_waitcnt lgkmcnt(0)
	v_mfma_f32_32x32x16_bf16 v[112:127], v[136:139], v[144:147], v[112:127]
	ds_read_b128 v[160:163], v248
	v_mfma_f32_32x32x16_bf16 v[80:95], v[136:139], v[148:151], v[80:95]
	ds_read_b128 v[164:167], v249 offset:8192
	v_mfma_f32_32x32x16_bf16 v[48:63], v[136:139], v[152:155], v[48:63]
	ds_read_b128 v[176:179], v248 offset:2048
	v_mfma_f32_32x32x16_bf16 v[16:31], v[136:139], v[156:159], v[16:31]
	ds_read_b128 v[180:183], v249 offset:10240
	v_mfma_f32_32x32x16_bf16 v[96:111], v[140:143], v[144:147], v[96:111]
	ds_read_b128 v[184:187], v249 offset:12288
	v_mfma_f32_32x32x16_bf16 v[64:79], v[140:143], v[148:151], v[64:79]
	ds_read_b128 v[188:191], v249 offset:14336
	v_mfma_f32_32x32x16_bf16 v[32:47], v[140:143], v[152:155], v[32:47]
	v_mfma_f32_32x32x16_bf16 v[0:15], v[140:143], v[156:159], v[0:15]
	s_cmp_lg_u32 s9, 0
	s_cbranch_scc0 .Lip3_exit_a
	s_waitcnt vmcnt(6)
	s_waitcnt lgkmcnt(0)
	s_barrier
	ds_read_b128 v[136:139], v238
	ds_read_b128 v[140:143], v238 offset:2048
	ds_read_b128 v[144:147], v239 offset:8192
	ds_read_b128 v[148:151], v239 offset:10240
	ds_read_b128 v[152:155], v239 offset:12288
	ds_read_b128 v[156:159], v239 offset:14336
	s_mul_i32 s29, s8, 0x6000
	s_add_i32 s101, s29, s100
	s_add_i32 s29, s28, 1
	s_cmp_lg_u32 s28, 2
	s_cselect_b32 s28, s29, 0
	s_add_i32 s29, s8, 1
	s_cmp_lg_u32 s8, 2
	s_cselect_b32 s8, s29, 0
	s_add_i32 s9, s9, -1
	s_add_u32 s6, s6, 0x120000
	s_addc_u32 s7, s7, 0
	s_add_u32 s4, s4, 0x38000
	s_addc_u32 s5, s5, 0
	s_mov_b32 m0, s101
	v_mfma_f32_32x32x16_bf16 v[112:127], v[160:163], v[164:167], v[112:127]
	global_load_lds_dwordx4 v170, s[4:5]
	s_add_u32 m0, s101, 0x1000
	v_mfma_f32_32x32x16_bf16 v[80:95], v[160:163], v[180:183], v[80:95]
	global_load_lds_dwordx4 v171, s[4:5]
	s_add_u32 m0, s101, 0x2000
	v_mfma_f32_32x32x16_bf16 v[48:63], v[160:163], v[184:187], v[48:63]
	global_load_lds_dwordx4 v172, s[6:7]
	s_add_u32 m0, s101, 0x3000
	v_mfma_f32_32x32x16_bf16 v[16:31], v[160:163], v[188:191], v[16:31]
	global_load_lds_dwordx4 v173, s[6:7]
	s_add_u32 m0, s101, 0x4000
	v_mfma_f32_32x32x16_bf16 v[96:111], v[176:179], v[164:167], v[96:111]
	global_load_lds_dwordx4 v174, s[6:7]
	s_add_u32 m0, s101, 0x5000
	v_mfma_f32_32x32x16_bf16 v[64:79], v[176:179], v[180:183], v[64:79]
	global_load_lds_dwordx4 v175, s[6:7]
	v_mfma_f32_32x32x16_bf16 v[32:47], v[176:179], v[184:187], v[32:47]
	v_mfma_f32_32x32x16_bf16 v[0:15], v[176:179], v[188:191], v[0:15]
	s_waitcnt lgkmcnt(0)
	v_mfma_f32_32x32x16_bf16 v[112:127], v[136:139], v[144:147], v[112:127]
	ds_read_b128 v[160:163], v240
	v_mfma_f32_32x32x16_bf16 v[80:95], v[136:139], v[148:151], v[80:95]
	ds_read_b128 v[164:167], v241 offset:8192
	v_mfma_f32_32x32x16_bf16 v[48:63], v[136:139], v[152:155], v[48:63]
	ds_read_b128 v[176:179], v240 offset:2048
	v_mfma_f32_32x32x16_bf16 v[16:31], v[136:139], v[156:159], v[16:31]
	ds_read_b128 v[180:183], v241 offset:10240
	v_mfma_f32_32x32x16_bf16 v[96:111], v[140:143], v[144:147], v[96:111]
	ds_read_b128 v[184:187], v241 offset:12288
	v_mfma_f32_32x32x16_bf16 v[64:79], v[140:143], v[148:151], v[64:79]
	ds_read_b128 v[188:191], v241 offset:14336
	v_mfma_f32_32x32x16_bf16 v[32:47], v[140:143], v[152:155], v[32:47]
	v_mfma_f32_32x32x16_bf16 v[0:15], v[140:143], v[156:159], v[0:15]
	s_cmp_lg_u32 s9, 0
	s_cbranch_scc1 .LBB0_202
; template <bool VMODE, int TJ>
; DI void gemm_mainloop(const bf16_t* __restrict__ W, const bf16_t* __restrict__ X, int NW, char* smem, f32x16 (&acc)[2][TJ]) {
;     ...
;         for (int ks = 0; ks < 32; ++ks) {
;             if (ks < 31) asm volatile("s_waitcnt vmcnt(6)" ::: "memory");
;             else asm volatile("s_waitcnt vmcnt(0)" ::: "memory");
;             __builtin_amdgcn_s_barrier();
;             const char* sw = smem + bc * STAGE + wf * 64 * 64;
;             const char* sx = smem + bc * STAGE + 8192 + wt * (32 * TJ) * 64;
;             bf16x8 fw[2], fx[TJ], gw[2], gx[TJ];
; #pragma unroll
;             for (int i = 0; i < 2; ++i) fw[i] = *(const bf16x8*)(sw + i * 32 * 64 + fo0);
; #pragma unroll
;             for (int j = 0; j < TJ; ++j) fx[j] = *(const bf16x8*)(sx + j * 32 * 64 + fo0);
;             __builtin_amdgcn_sched_barrier(0);
;             if (ks + 2 < 32) G_ISSUE(ks + 2, bn);
;             __builtin_amdgcn_sched_barrier(0);
; #pragma unroll
;             for (int i = 0; i < 2; ++i) gw[i] = *(const bf16x8*)(sw + i * 32 * 64 + fo1);
; #pragma unroll
;             for (int j = 0; j < TJ; ++j) gx[j] = *(const bf16x8*)(sx + j * 32 * 64 + fo1);
; #pragma unroll
;             for (int i = 0; i < 2; ++i)
; #pragma unroll
;                 for (int j = 0; j < TJ; ++j) acc[i][j] = VMODE ? MFMA(fx[j], fw[i], acc[i][j]) : MFMA(fw[i], fx[j], acc[i][j]);
; #pragma unroll
;             for (int i = 0; i < 2; ++i)
; #pragma unroll
;                 for (int j = 0; j < TJ; ++j) acc[i][j] = VMODE ? MFMA(gx[j], gw[i], acc[i][j]) : MFMA(gw[i], gx[j], acc[i][j]);
;             bc = (bc == 2) ? 0 : bc + 1; bn = (bn == 2) ? 0 : bn + 1;
;         }
;     }
;     ...
;     __syncthreads();
; DI void epi_inproj(const Params& p, int l, int mtile, int n0, f32x16 (&acc)[2][4], char* smem) {
;     ...
;     int type; const float* nwt = nullptr; bool rope = false;
;     if (n0 < 256) { type = 2; nwt = p.dqn + l * 32; rope = true; }
;     else if (n0 < 512) { type = 2; nwt = p.dkn + l * 32; rope = true; }
;     else if (n0 < 1024) { type = 1; }
;     else if (n0 < 1408) { type = 3; nwt = p.gqn + l * 64; rope = true; }
;     else if (n0 < 1536) { type = 3; nwt = p.gkn + l * 64; rope = true; }
;     else if (n0 < 2048) { type = 1; }
;     else if (n0 < 2432) { type = 3; nwt = p.nqn + l * 64; }
;     else if (n0 < 2816) { type = 3; nwt = p.nkn + l * 64; }
;     else { type = 1; }
.Lip3_exit_a:
	s_waitcnt lgkmcnt(0)
	v_mfma_f32_32x32x16_bf16 v[112:127], v[160:163], v[164:167], v[112:127]
	v_mfma_f32_32x32x16_bf16 v[80:95], v[160:163], v[180:183], v[80:95]
	v_mfma_f32_32x32x16_bf16 v[48:63], v[160:163], v[184:187], v[48:63]
	v_mfma_f32_32x32x16_bf16 v[16:31], v[160:163], v[188:191], v[16:31]
	v_mfma_f32_32x32x16_bf16 v[96:111], v[176:179], v[164:167], v[96:111]
	v_mfma_f32_32x32x16_bf16 v[64:79], v[176:179], v[180:183], v[64:79]
	v_mfma_f32_32x32x16_bf16 v[32:47], v[176:179], v[184:187], v[32:47]
	v_mfma_f32_32x32x16_bf16 v[0:15], v[176:179], v[188:191], v[0:15]
	v_add_u32_e32 v154, 32, v134
	v_add_u32_e32 v133, 32, v133
	v_add_u32_e32 v155, v154, v131
	v_add_u32_e32 v156, v133, v131
	s_waitcnt vmcnt(6)
	s_barrier
	ds_read_b128 v[134:137], v155
	ds_read_b128 v[138:141], v155 offset:2048
	ds_read_b128 v[128:131], v156 offset:8192
	ds_read_b128 v[142:145], v156 offset:10240
	ds_read_b128 v[146:149], v156 offset:12288
	ds_read_b128 v[150:153], v156 offset:14336
	v_add_u32_e32 v160, v154, v132
	s_waitcnt lgkmcnt(0)
	v_mfma_f32_32x32x16_bf16 v[112:127], v[134:137], v[128:131], v[112:127]
	v_add_u32_e32 v161, v133, v132
	v_mfma_f32_32x32x16_bf16 v[96:111], v[138:141], v[128:131], v[96:111]
	ds_read_b128 v[128:131], v160
	v_mfma_f32_32x32x16_bf16 v[80:95], v[134:137], v[142:145], v[80:95]
	v_mfma_f32_32x32x16_bf16 v[48:63], v[134:137], v[146:149], v[48:63]
	v_mfma_f32_32x32x16_bf16 v[16:31], v[134:137], v[150:153], v[16:31]
	v_mfma_f32_32x32x16_bf16 v[64:79], v[138:141], v[142:145], v[64:79]
	v_mfma_f32_32x32x16_bf16 v[32:47], v[138:141], v[146:149], v[32:47]
	v_mfma_f32_32x32x16_bf16 v[0:15], v[138:141], v[150:153], v[0:15]
	ds_read_b128 v[132:135], v161 offset:8192
	ds_read_b128 v[136:139], v160 offset:2048
	ds_read_b128 v[140:143], v161 offset:10240
	ds_read_b128 v[144:147], v161 offset:12288
	ds_read_b128 v[148:151], v161 offset:14336
	s_waitcnt vmcnt(0)
	s_barrier
	s_waitcnt lgkmcnt(0)
	v_mfma_f32_32x32x16_bf16 v[112:127], v[128:131], v[132:135], v[112:127]
	v_mfma_f32_32x32x16_bf16 v[80:95], v[128:131], v[140:143], v[80:95]
	v_mfma_f32_32x32x16_bf16 v[48:63], v[128:131], v[144:147], v[48:63]
	v_mfma_f32_32x32x16_bf16 v[16:31], v[128:131], v[148:151], v[16:31]
	v_mfma_f32_32x32x16_bf16 v[96:111], v[136:139], v[132:135], v[96:111]
	v_mfma_f32_32x32x16_bf16 v[64:79], v[136:139], v[140:143], v[64:79]
	v_mfma_f32_32x32x16_bf16 v[32:47], v[136:139], v[144:147], v[32:47]
	ds_read_b128 v[128:131], v155 offset:24576
	ds_read_b128 v[132:135], v155 offset:26624
	ds_read_b128 v[140:143], v156 offset:32768
	ds_read_b128 v[144:147], v156 offset:34816
	ds_read_b128 v[152:155], v156 offset:36864
	ds_read_b128 v[156:159], v156 offset:38912
	v_mfma_f32_32x32x16_bf16 v[0:15], v[136:139], v[148:151], v[0:15]
	s_waitcnt lgkmcnt(0)
	v_mfma_f32_32x32x16_bf16 v[112:127], v[128:131], v[140:143], v[112:127]
	s_cmp_lt_i32 s99, 2
	s_cselect_b64 s[40:41], -1, 0
	s_cmp_gt_i32 s99, 1
	s_mov_b64 s[6:7], -1
	v_mfma_f32_32x32x16_bf16 v[80:95], v[128:131], v[144:147], v[80:95]
	v_mfma_f32_32x32x16_bf16 v[48:63], v[128:131], v[152:155], v[48:63]
	v_mfma_f32_32x32x16_bf16 v[16:31], v[128:131], v[156:159], v[16:31]
	v_mfma_f32_32x32x16_bf16 v[96:111], v[132:135], v[140:143], v[96:111]
	v_mfma_f32_32x32x16_bf16 v[64:79], v[132:135], v[144:147], v[64:79]
	v_mfma_f32_32x32x16_bf16 v[32:47], v[132:135], v[152:155], v[32:47]
	v_mfma_f32_32x32x16_bf16 v[0:15], v[132:135], v[156:159], v[0:15]
	ds_read_b128 v[128:131], v160 offset:24576
	ds_read_b128 v[132:135], v161 offset:32768
	ds_read_b128 v[136:139], v160 offset:26624
	ds_read_b128 v[140:143], v161 offset:34816
	ds_read_b128 v[144:147], v161 offset:36864
	ds_read_b128 v[148:151], v161 offset:38912
	s_waitcnt vmcnt(0) lgkmcnt(0)
	s_barrier
	v_mfma_f32_32x32x16_bf16 v[112:127], v[128:131], v[132:135], v[112:127]
	v_mfma_f32_32x32x16_bf16 v[80:95], v[128:131], v[140:143], v[80:95]
	v_mfma_f32_32x32x16_bf16 v[48:63], v[128:131], v[144:147], v[48:63]
	v_mfma_f32_32x32x16_bf16 v[16:31], v[128:131], v[148:151], v[16:31]
	v_mfma_f32_32x32x16_bf16 v[96:111], v[136:139], v[132:135], v[96:111]
	v_mfma_f32_32x32x16_bf16 v[64:79], v[136:139], v[140:143], v[64:79]
	v_mfma_f32_32x32x16_bf16 v[32:47], v[136:139], v[144:147], v[32:47]
	v_mov_b32_e32 v145, v200
	v_mfma_f32_32x32x16_bf16 v[0:15], v[136:139], v[148:151], v[0:15]
	s_cbranch_scc0 .LBB0_223
	s_cmpk_gt_u32 s58, 0x1ff
	s_cbranch_scc0 .LBB0_220
	s_cmpk_lt_u32 s58, 0x400
	s_mov_b64 s[6:7], 0
	s_cbranch_scc1 .LBB0_214
	s_cmpk_gt_u32 s58, 0x57f
	s_mov_b64 s[42:43], -1
	s_cbranch_scc0 .LBB0_218
	s_cmpk_gt_u32 s58, 0x5ff
	s_mov_b64 s[34:35], -1
	s_cbranch_scc0 .LBB0_216
	s_cmpk_lt_u32 s58, 0x800
	s_mov_b64 s[34:35], 0
	s_cbranch_scc1 .LBB0_215
	s_cmpk_gt_u32 s58, 0x97f
	s_cbranch_scc0 .LBB0_212
	s_cmpk_gt_u32 s58, 0xaff
	s_mov_b64 s[42:43], 0
	s_cbranch_scc1 .LBB0_291
	s_load_dwordx2 s[4:5], s[0:1], 0x98
	v_readlane_b32 s8, v255, 36
	v_readlane_b32 s9, v255, 37
	s_lshl_b64 s[8:9], s[8:9], 2
	s_mov_b64 s[28:29], -1
	s_waitcnt lgkmcnt(0)
	s_add_u32 s4, s4, s8
	s_addc_u32 s5, s5, s9
	s_mov_b64 s[8:9], 0

; DI int otid() { int t = threadIdx.x; asm volatile("" : "+v"(t)); return t; }
; #define G_ISSUE(ks_, buf_) do { \
;     const bf16_t* wq_ = wp + (ks_) * wks; const bf16_t* xq_ = xp + (ks_) * xks; char* lb_ = ld + (buf_) * STAGE; \
;     dma16(wq_, lb_); dma16(wq_ + 2048, lb_ + 4096); \
;     _Pragma("unroll") for (int i_ = 0; i_ < TJ; ++i_) dma16(xq_ + i_ * 2048, lb_ + 8192 + i_ * 4096); } while (0)
; template <bool VMODE, int TJ>
; DI void gemm_mainloop(const bf16_t* __restrict__ W, const bf16_t* __restrict__ X, int NW, char* smem, f32x16 (&acc)[2][TJ]) {
;     constexpr int XROWS = 64 * TJ, STAGE = (128 + XROWS) * 64, NPW = 2 + TJ;
;     const int tid = otid(), lane = tid & 63, wave = tid >> 6, r = lane & 31, h = lane >> 5, wf = wave & 1, wt = wave >> 1;
;     const int goff = (16 * wave + (lane >> 2)) * 32 + (((lane & 3) ^ (lane >> 4)) << 3);
;     const bf16_t* wp = W + goff;
;     const bf16_t* xp = X + goff;
;     const size_t wks = (size_t)NW * 32, xks = (size_t)NTOK * 32;
;     char* ld = smem + tid * 16;
;     ...
;     const int xr = (r >> 2) & 3;
;     const int fo0 = r * 64 + (((0 + h) ^ xr) << 4), fo1 = r * 64 + (((2 + h) ^ xr) << 4);
;     __syncthreads();
;     ...
;         G_ISSUE(0, 0);
;         G_ISSUE(1, 1);
;         int bc = 0, bn = 2;
.LBB0_287:
	s_and_b64 vcc, exec, s[4:5]
	s_cbranch_vccz .LBB0_185
	v_mov_b32_e32 v4, v200
	s_movk_i32 s4, 0xffe0
	v_bfe_u32 v1, v4, 4, 2
	v_bitop3_b32 v1, v1, v4, 3 bitop3:0x78
	v_lshlrev_b32_e32 v0, 3, v4
	v_lshlrev_b32_e32 v1, 3, v1
	v_and_or_b32 v0, v0, s4, v1
	v_bfe_u32 v5, v4, 5, 1
	v_ashrrev_i32_e32 v1, 31, v0
	v_lshl_add_u32 v130, v4, 4, 32
	v_bfe_u32 v7, v4, 2, 2
	v_lshlrev_b64 v[128:129], 1, v[0:1]
	v_bitop3_b32 v9, v5, v7, 2 bitop3:0x36
	v_readfirstlane_b32 s5, v130
	v_add_u32_e32 v7, 0x1000, v130
	v_lshl_add_u64 v[0:1], s[52:53], 0, v[128:129]
	v_lshrrev_b32_e32 v6, 2, v4
	s_mov_b32 m0, s5
	v_readfirstlane_b32 s5, v7
	v_lshlrev_b32_e32 v8, 6, v4
	v_bitop3_b32 v6, v5, v6, 3 bitop3:0x78
	s_barrier
	global_load_lds_dwordx4 v[0:1], off
	v_lshl_add_u64 v[4:5], v[0:1], 0, s[26:27]
	s_mov_b32 m0, s5
	v_add_u32_e32 v7, 0x3000, v130
	global_load_lds_dwordx4 v[4:5], off
	v_add_u32_e32 v4, 0x2000, v130
	v_lshl_add_u64 v[2:3], s[56:57], 0, v[128:129]
	v_readfirstlane_b32 s5, v4
	s_mov_b32 m0, s5
	v_readfirstlane_b32 s5, v7
	v_add_u32_e32 v7, 0x4000, v130
	global_load_lds_dwordx4 v[2:3], off
	v_lshl_add_u64 v[4:5], v[2:3], 0, s[26:27]
	s_mov_b32 m0, s5
	v_readfirstlane_b32 s5, v7
	v_add_u32_e32 v7, 0x5000, v130
	global_load_lds_dwordx4 v[4:5], off
	v_lshl_add_u64 v[4:5], v[2:3], 0, s[16:17]
	s_mov_b32 m0, s5
	v_readfirstlane_b32 s5, v7
	v_add_u32_e32 v11, 0x6000, v130
	global_load_lds_dwordx4 v[4:5], off
	v_lshl_add_u64 v[4:5], v[2:3], 0, s[90:91]
	s_mov_b32 m0, s5
	s_mov_b64 s[6:7], 0x38000
	v_readfirstlane_b32 s5, v11
	global_load_lds_dwordx4 v[4:5], off
	v_lshl_add_u64 v[4:5], v[0:1], 0, s[6:7]
	s_mov_b32 m0, s5
	v_and_b32_e32 v10, 0x7c0, v8
	s_mov_b64 s[6:7], 0x120000
	global_load_lds_dwordx4 v[4:5], off
	v_add_u32_e32 v4, 0x7000, v130
	v_lshl_or_b32 v131, v6, 4, v10
	v_lshl_add_u64 v[6:7], v[2:3], 0, s[6:7]
	s_mov_b64 s[6:7], 0x39000
	v_readfirstlane_b32 s5, v4
	v_lshl_add_u64 v[0:1], v[0:1], 0, s[6:7]
	s_mov_b32 m0, s5
	v_add_u32_e32 v4, 0x9000, v130
	global_load_lds_dwordx4 v[0:1], off
	v_add_u32_e32 v0, 0x8000, v130
	s_mov_b64 s[6:7], 0x121000
	v_readfirstlane_b32 s5, v0
	s_mov_b32 m0, s5
	v_readfirstlane_b32 s5, v4
	v_add_u32_e32 v4, 0xa000, v130
	global_load_lds_dwordx4 v[6:7], off
	v_lshl_add_u64 v[0:1], v[2:3], 0, s[6:7]
	s_mov_b32 m0, s5
	s_mov_b64 s[6:7], 0x122000
	v_readfirstlane_b32 s5, v4
	global_load_lds_dwordx4 v[0:1], off
	v_lshl_add_u64 v[0:1], v[2:3], 0, s[6:7]
	s_mov_b32 m0, s5
	s_mov_b64 s[6:7], 0x123000
	global_load_lds_dwordx4 v[0:1], off
	v_lshl_add_u64 v[0:1], v[2:3], 0, s[6:7]
	v_add_u32_e32 v2, 0xb000, v130
	s_mov_b32 s4, 2
	v_readfirstlane_b32 s5, v2
	s_mov_b32 m0, s5
	v_lshl_or_b32 v132, v9, 4, v10
	global_load_lds_dwordx4 v[0:1], off
	v_mov_b32_e32 v0, 0
	v_and_b32_e32 v134, 0x1000, v8
	v_and_b32_e32 v133, 0xffffe000, v8
	s_mov_b32 s6, 0
	s_mov_b32 s5, 30
	v_mov_b32_e32 v1, v0
	v_mov_b32_e32 v2, v0
	v_mov_b32_e32 v3, v0
	v_mov_b32_e32 v4, v0
	v_mov_b32_e32 v5, v0
	v_mov_b32_e32 v6, v0
	v_mov_b32_e32 v7, v0
	v_mov_b32_e32 v8, v0
	v_mov_b32_e32 v9, v0
	v_mov_b32_e32 v10, v0
	v_mov_b32_e32 v11, v0
	v_mov_b32_e32 v12, v0
	v_mov_b32_e32 v13, v0
	v_mov_b32_e32 v14, v0
	v_mov_b32_e32 v15, v0
	v_mov_b32_e32 v16, v0
	v_mov_b32_e32 v17, v0
	v_mov_b32_e32 v18, v0
	v_mov_b32_e32 v19, v0
	v_mov_b32_e32 v20, v0
	v_mov_b32_e32 v21, v0
	v_mov_b32_e32 v22, v0
	v_mov_b32_e32 v23, v0
	v_mov_b32_e32 v24, v0
	v_mov_b32_e32 v25, v0
	v_mov_b32_e32 v26, v0
	v_mov_b32_e32 v27, v0
	v_mov_b32_e32 v28, v0
	v_mov_b32_e32 v29, v0
	v_mov_b32_e32 v30, v0
	v_mov_b32_e32 v31, v0
	v_mov_b32_e32 v32, v0
	v_mov_b32_e32 v33, v0
	v_mov_b32_e32 v34, v0
	v_mov_b32_e32 v35, v0
	v_mov_b32_e32 v36, v0
	v_mov_b32_e32 v37, v0
	v_mov_b32_e32 v38, v0
	v_mov_b32_e32 v39, v0
	v_mov_b32_e32 v40, v0
	v_mov_b32_e32 v41, v0
	v_mov_b32_e32 v42, v0
	v_mov_b32_e32 v43, v0
	v_mov_b32_e32 v44, v0
	v_mov_b32_e32 v45, v0
	v_mov_b32_e32 v46, v0
	v_mov_b32_e32 v47, v0
	v_mov_b32_e32 v48, v0
	v_mov_b32_e32 v49, v0
	v_mov_b32_e32 v50, v0
	v_mov_b32_e32 v51, v0
	v_mov_b32_e32 v52, v0
	v_mov_b32_e32 v53, v0
	v_mov_b32_e32 v54, v0
	v_mov_b32_e32 v55, v0
	v_mov_b32_e32 v56, v0
	v_mov_b32_e32 v57, v0
	v_mov_b32_e32 v58, v0
	v_mov_b32_e32 v59, v0
	v_mov_b32_e32 v60, v0
	v_mov_b32_e32 v61, v0
	v_mov_b32_e32 v62, v0
	v_mov_b32_e32 v63, v0
	v_mov_b32_e32 v64, v0
	v_mov_b32_e32 v65, v0
	v_mov_b32_e32 v66, v0
	v_mov_b32_e32 v67, v0
	v_mov_b32_e32 v68, v0
	v_mov_b32_e32 v69, v0
	v_mov_b32_e32 v70, v0
	v_mov_b32_e32 v71, v0
	v_mov_b32_e32 v72, v0
	v_mov_b32_e32 v73, v0
	v_mov_b32_e32 v74, v0
	v_mov_b32_e32 v75, v0
	v_mov_b32_e32 v76, v0
	v_mov_b32_e32 v77, v0
	v_mov_b32_e32 v78, v0
	v_mov_b32_e32 v79, v0
	v_mov_b32_e32 v80, v0
	v_mov_b32_e32 v81, v0
	v_mov_b32_e32 v82, v0
	v_mov_b32_e32 v83, v0
	v_mov_b32_e32 v84, v0
	v_mov_b32_e32 v85, v0
	v_mov_b32_e32 v86, v0
	v_mov_b32_e32 v87, v0
	v_mov_b32_e32 v88, v0
	v_mov_b32_e32 v89, v0
	v_mov_b32_e32 v90, v0
	v_mov_b32_e32 v91, v0
	v_mov_b32_e32 v92, v0
	v_mov_b32_e32 v93, v0
	v_mov_b32_e32 v94, v0
	v_mov_b32_e32 v95, v0
	v_mov_b32_e32 v96, v0
	v_mov_b32_e32 v97, v0
	v_mov_b32_e32 v98, v0
	v_mov_b32_e32 v99, v0
	v_mov_b32_e32 v100, v0
	v_mov_b32_e32 v101, v0
	v_mov_b32_e32 v102, v0
	v_mov_b32_e32 v103, v0
	v_mov_b32_e32 v104, v0
	v_mov_b32_e32 v105, v0
	v_mov_b32_e32 v106, v0
	v_mov_b32_e32 v107, v0
	v_mov_b32_e32 v108, v0
	v_mov_b32_e32 v109, v0
	v_mov_b32_e32 v110, v0
	v_mov_b32_e32 v111, v0
	v_mov_b32_e32 v112, v0
	v_mov_b32_e32 v113, v0
	v_mov_b32_e32 v114, v0
	v_mov_b32_e32 v115, v0
	v_mov_b32_e32 v116, v0
	v_mov_b32_e32 v117, v0
	v_mov_b32_e32 v118, v0
	v_mov_b32_e32 v119, v0
	v_mov_b32_e32 v120, v0
	v_mov_b32_e32 v121, v0
	v_mov_b32_e32 v122, v0
	v_mov_b32_e32 v123, v0
	v_mov_b32_e32 v124, v0
	v_mov_b32_e32 v125, v0
	v_mov_b32_e32 v126, v0
	v_mov_b32_e32 v127, v0
	v_readfirstlane_b32 s100, v130
	v_add_u32_e32 v170, 0x38000, v128
	v_add_u32_e32 v171, 0x39000, v128
	v_add_u32_e32 v172, 0x120000, v128
	v_add_u32_e32 v173, 0x121000, v128
	v_add_u32_e32 v174, 0x122000, v128
	v_add_u32_e32 v175, 0x123000, v128
	v_add_u32_e32 v238, v134, v131
	v_add_u32_e32 v239, v133, v131
	v_add_u32_e32 v240, v134, v132
	v_add_u32_e32 v241, v133, v132
	v_add_u32_e32 v238, 0x20, v238
	v_add_u32_e32 v239, 0x20, v239
	v_add_u32_e32 v240, 0x20, v240
	v_add_u32_e32 v241, 0x20, v241
	v_add_u32_e32 v242, v134, v131
	v_add_u32_e32 v243, v133, v131
	v_add_u32_e32 v244, v134, v132
	v_add_u32_e32 v245, v133, v132
	v_add_u32_e32 v242, 0x6020, v242
	v_add_u32_e32 v243, 0x6020, v243
	v_add_u32_e32 v244, 0x6020, v244
	v_add_u32_e32 v245, 0x6020, v245
	v_add_u32_e32 v246, v134, v131
	v_add_u32_e32 v247, v133, v131
	v_add_u32_e32 v248, v134, v132
	v_add_u32_e32 v249, v133, v132
	v_add_u32_e32 v246, 0xc020, v246
	v_add_u32_e32 v247, 0xc020, v247
	v_add_u32_e32 v248, 0xc020, v248
	v_add_u32_e32 v249, 0xc020, v249
	s_mul_i32 s7, s6, 0x6000
	s_add_i32 s7, s7, 32
	v_add_u32_e32 v135, s7, v134
	v_add_u32_e32 v168, s7, v133
	v_add_u32_e32 v140, v135, v131
	v_add_u32_e32 v156, v168, v131
	s_waitcnt vmcnt(6)
	s_barrier
; #define MFMA(a, b, c) __builtin_amdgcn_mfma_f32_32x32x16_bf16((a), (b), (c), 0, 0, 0)
; #define G_ISSUE(ks_, buf_) do { \
;     const bf16_t* wq_ = wp + (ks_) * wks; const bf16_t* xq_ = xp + (ks_) * xks; char* lb_ = ld + (buf_) * STAGE; \
;     dma16(wq_, lb_); dma16(wq_ + 2048, lb_ + 4096); \
;     _Pragma("unroll") for (int i_ = 0; i_ < TJ; ++i_) dma16(xq_ + i_ * 2048, lb_ + 8192 + i_ * 4096); } while (0)
; template <bool VMODE, int TJ>
; DI void gemm_mainloop(const bf16_t* __restrict__ W, const bf16_t* __restrict__ X, int NW, char* smem, f32x16 (&acc)[2][TJ]) {
;     ...
;         for (int ks = 0; ks < 32; ++ks) {
;             if (ks < 31) asm volatile("s_waitcnt vmcnt(6)" ::: "memory");
;             else asm volatile("s_waitcnt vmcnt(0)" ::: "memory");
;             __builtin_amdgcn_s_barrier();
;             const char* sw = smem + bc * STAGE + wf * 64 * 64;
;             const char* sx = smem + bc * STAGE + 8192 + wt * (32 * TJ) * 64;
;             bf16x8 fw[2], fx[TJ], gw[2], gx[TJ];
; #pragma unroll
;             for (int i = 0; i < 2; ++i) fw[i] = *(const bf16x8*)(sw + i * 32 * 64 + fo0);
; #pragma unroll
;             for (int j = 0; j < TJ; ++j) fx[j] = *(const bf16x8*)(sx + j * 32 * 64 + fo0);
;             __builtin_amdgcn_sched_barrier(0);
;             if (ks + 2 < 32) G_ISSUE(ks + 2, bn);
;             __builtin_amdgcn_sched_barrier(0);
; #pragma unroll
;             for (int i = 0; i < 2; ++i) gw[i] = *(const bf16x8*)(sw + i * 32 * 64 + fo1);
; #pragma unroll
;             for (int j = 0; j < TJ; ++j) gx[j] = *(const bf16x8*)(sx + j * 32 * 64 + fo1);
; #pragma unroll
;             for (int i = 0; i < 2; ++i)
; #pragma unroll
;                 for (int j = 0; j < TJ; ++j) acc[i][j] = VMODE ? MFMA(fx[j], fw[i], acc[i][j]) : MFMA(fw[i], fx[j], acc[i][j]);
; #pragma unroll
;             for (int i = 0; i < 2; ++i)
; #pragma unroll
;                 for (int j = 0; j < TJ; ++j) acc[i][j] = VMODE ? MFMA(gx[j], gw[i], acc[i][j]) : MFMA(gw[i], gx[j], acc[i][j]);
;             bc = (bc == 2) ? 0 : bc + 1; bn = (bn == 2) ? 0 : bn + 1;
;         }
	ds_read_b128 v[136:139], v140
	ds_read_b128 v[140:143], v140 offset:2048
	ds_read_b128 v[144:147], v156 offset:8192
	ds_read_b128 v[148:151], v156 offset:10240
	ds_read_b128 v[152:155], v156 offset:12288
	ds_read_b128 v[156:159], v156 offset:14336
	s_mul_i32 s7, s4, 0x6000
	s_add_i32 s101, s7, s100
	s_add_i32 s7, s6, 1
	s_cmp_lg_u32 s6, 2
	s_cselect_b32 s6, s7, 0
	s_add_i32 s7, s4, 1
	s_cmp_lg_u32 s4, 2
	s_cselect_b32 s4, s7, 0
	s_add_i32 s5, s5, -1
	s_add_u32 s56, s56, 0x120000
	s_addc_u32 s57, s57, 0
	s_add_u32 s52, s52, 0x38000
	s_addc_u32 s53, s53, 0
	v_add_u32_e32 v169, v135, v132
	v_add_u32_e32 v192, v168, v132
	s_mov_b32 m0, s101
	s_waitcnt lgkmcnt(0)
	v_mfma_f32_32x32x16_bf16 v[112:127], v[144:147], v[136:139], v[112:127]
	global_load_lds_dwordx4 v170, s[52:53]
	s_add_u32 m0, s101, 0x1000
	ds_read_b128 v[160:163], v192 offset:8192
	v_mfma_f32_32x32x16_bf16 v[96:111], v[148:151], v[136:139], v[96:111]
	global_load_lds_dwordx4 v171, s[52:53]
	s_add_u32 m0, s101, 0x2000
	ds_read_b128 v[164:167], v169
	v_mfma_f32_32x32x16_bf16 v[80:95], v[152:155], v[136:139], v[80:95]
	global_load_lds_dwordx4 v172, s[56:57]
	s_add_u32 m0, s101, 0x3000
	ds_read_b128 v[176:179], v169 offset:2048
	v_mfma_f32_32x32x16_bf16 v[64:79], v[156:159], v[136:139], v[64:79]
	global_load_lds_dwordx4 v173, s[56:57]
	s_add_u32 m0, s101, 0x4000
	ds_read_b128 v[180:183], v192 offset:10240
	v_mfma_f32_32x32x16_bf16 v[48:63], v[144:147], v[140:143], v[48:63]
	global_load_lds_dwordx4 v174, s[56:57]
	s_add_u32 m0, s101, 0x5000
	ds_read_b128 v[184:187], v192 offset:12288
	v_mfma_f32_32x32x16_bf16 v[32:47], v[148:151], v[140:143], v[32:47]
	global_load_lds_dwordx4 v175, s[56:57]
	ds_read_b128 v[188:191], v192 offset:14336
	v_mfma_f32_32x32x16_bf16 v[16:31], v[152:155], v[140:143], v[16:31]
	v_mfma_f32_32x32x16_bf16 v[0:15], v[156:159], v[140:143], v[0:15]
.LBB0_289:
	s_waitcnt vmcnt(6)
	s_waitcnt lgkmcnt(0)
	s_barrier
	ds_read_b128 v[136:139], v242
	ds_read_b128 v[140:143], v242 offset:2048
	ds_read_b128 v[144:147], v243 offset:8192
	ds_read_b128 v[148:151], v243 offset:10240
	ds_read_b128 v[152:155], v243 offset:12288
	ds_read_b128 v[156:159], v243 offset:14336
	s_mul_i32 s7, s4, 0x6000
	s_add_i32 s101, s7, s100
	s_add_i32 s7, s6, 1
	s_cmp_lg_u32 s6, 2
	s_cselect_b32 s6, s7, 0
	s_add_i32 s7, s4, 1
	s_cmp_lg_u32 s4, 2
	s_cselect_b32 s4, s7, 0
	s_add_i32 s5, s5, -1
	s_add_u32 s56, s56, 0x120000
	s_addc_u32 s57, s57, 0
	s_add_u32 s52, s52, 0x38000
	s_addc_u32 s53, s53, 0
	s_mov_b32 m0, s101
	v_mfma_f32_32x32x16_bf16 v[112:127], v[160:163], v[164:167], v[112:127]
	global_load_lds_dwordx4 v170, s[52:53]
	s_add_u32 m0, s101, 0x1000
	v_mfma_f32_32x32x16_bf16 v[96:111], v[180:183], v[164:167], v[96:111]
	global_load_lds_dwordx4 v171, s[52:53]
	s_add_u32 m0, s101, 0x2000
	v_mfma_f32_32x32x16_bf16 v[80:95], v[184:187], v[164:167], v[80:95]
	global_load_lds_dwordx4 v172, s[56:57]
	s_add_u32 m0, s101, 0x3000
	v_mfma_f32_32x32x16_bf16 v[64:79], v[188:191], v[164:167], v[64:79]
	global_load_lds_dwordx4 v173, s[56:57]
	s_add_u32 m0, s101, 0x4000
	v_mfma_f32_32x32x16_bf16 v[48:63], v[160:163], v[176:179], v[48:63]
	global_load_lds_dwordx4 v174, s[56:57]
	s_add_u32 m0, s101, 0x5000
	v_mfma_f32_32x32x16_bf16 v[32:47], v[180:183], v[176:179], v[32:47]
	global_load_lds_dwordx4 v175, s[56:57]
	v_mfma_f32_32x32x16_bf16 v[16:31], v[184:187], v[176:179], v[16:31]
	v_mfma_f32_32x32x16_bf16 v[0:15], v[188:191], v[176:179], v[0:15]
	s_waitcnt lgkmcnt(0)
	v_mfma_f32_32x32x16_bf16 v[112:127], v[144:147], v[136:139], v[112:127]
	ds_read_b128 v[160:163], v245 offset:8192
	v_mfma_f32_32x32x16_bf16 v[96:111], v[148:151], v[136:139], v[96:111]
	ds_read_b128 v[164:167], v244
	v_mfma_f32_32x32x16_bf16 v[80:95], v[152:155], v[136:139], v[80:95]
	ds_read_b128 v[176:179], v244 offset:2048
	v_mfma_f32_32x32x16_bf16 v[64:79], v[156:159], v[136:139], v[64:79]
	ds_read_b128 v[180:183], v245 offset:10240
	v_mfma_f32_32x32x16_bf16 v[48:63], v[144:147], v[140:143], v[48:63]
	ds_read_b128 v[184:187], v245 offset:12288
	v_mfma_f32_32x32x16_bf16 v[32:47], v[148:151], v[140:143], v[32:47]
	ds_read_b128 v[188:191], v245 offset:14336
	v_mfma_f32_32x32x16_bf16 v[16:31], v[152:155], v[140:143], v[16:31]
	v_mfma_f32_32x32x16_bf16 v[0:15], v[156:159], v[140:143], v[0:15]
	s_cmp_lg_u32 s5, 0
	s_cbranch_scc0 .Lip3_exit_b
	s_waitcnt vmcnt(6)
	s_waitcnt lgkmcnt(0)
	s_barrier
	ds_read_b128 v[136:139], v246
	ds_read_b128 v[140:143], v246 offset:2048
	ds_read_b128 v[144:147], v247 offset:8192
	ds_read_b128 v[148:151], v247 offset:10240
	ds_read_b128 v[152:155], v247 offset:12288
	ds_read_b128 v[156:159], v247 offset:14336
	s_mul_i32 s7, s4, 0x6000
	s_add_i32 s101, s7, s100
	s_add_i32 s7, s6, 1
	s_cmp_lg_u32 s6, 2
	s_cselect_b32 s6, s7, 0
	s_add_i32 s7, s4, 1
	s_cmp_lg_u32 s4, 2
	s_cselect_b32 s4, s7, 0
	s_add_i32 s5, s5, -1
	s_add_u32 s56, s56, 0x120000
	s_addc_u32 s57, s57, 0
	s_add_u32 s52, s52, 0x38000
	s_addc_u32 s53, s53, 0
	s_mov_b32 m0, s101
	v_mfma_f32_32x32x16_bf16 v[112:127], v[160:163], v[164:167], v[112:127]
	global_load_lds_dwordx4 v170, s[52:53]
	s_add_u32 m0, s101, 0x1000
	v_mfma_f32_32x32x16_bf16 v[96:111], v[180:183], v[164:167], v[96:111]
	global_load_lds_dwordx4 v171, s[52:53]
	s_add_u32 m0, s101, 0x2000
	v_mfma_f32_32x32x16_bf16 v[80:95], v[184:187], v[164:167], v[80:95]
	global_load_lds_dwordx4 v172, s[56:57]
	s_add_u32 m0, s101, 0x3000
	v_mfma_f32_32x32x16_bf16 v[64:79], v[188:191], v[164:167], v[64:79]
	global_load_lds_dwordx4 v173, s[56:57]
	s_add_u32 m0, s101, 0x4000
	v_mfma_f32_32x32x16_bf16 v[48:63], v[160:163], v[176:179], v[48:63]
	global_load_lds_dwordx4 v174, s[56:57]
	s_add_u32 m0, s101, 0x5000
	v_mfma_f32_32x32x16_bf16 v[32:47], v[180:183], v[176:179], v[32:47]
	global_load_lds_dwordx4 v175, s[56:57]
	v_mfma_f32_32x32x16_bf16 v[16:31], v[184:187], v[176:179], v[16:31]
	v_mfma_f32_32x32x16_bf16 v[0:15], v[188:191], v[176:179], v[0:15]
	s_waitcnt lgkmcnt(0)
	v_mfma_f32_32x32x16_bf16 v[112:127], v[144:147], v[136:139], v[112:127]
	ds_read_b128 v[160:163], v249 offset:8192
	v_mfma_f32_32x32x16_bf16 v[96:111], v[148:151], v[136:139], v[96:111]
	ds_read_b128 v[164:167], v248
	v_mfma_f32_32x32x16_bf16 v[80:95], v[152:155], v[136:139], v[80:95]
	ds_read_b128 v[176:179], v248 offset:2048
	v_mfma_f32_32x32x16_bf16 v[64:79], v[156:159], v[136:139], v[64:79]
	ds_read_b128 v[180:183], v249 offset:10240
	v_mfma_f32_32x32x16_bf16 v[48:63], v[144:147], v[140:143], v[48:63]
	ds_read_b128 v[184:187], v249 offset:12288
	v_mfma_f32_32x32x16_bf16 v[32:47], v[148:151], v[140:143], v[32:47]
	ds_read_b128 v[188:191], v249 offset:14336
	v_mfma_f32_32x32x16_bf16 v[16:31], v[152:155], v[140:143], v[16:31]
	v_mfma_f32_32x32x16_bf16 v[0:15], v[156:159], v[140:143], v[0:15]
	s_cmp_lg_u32 s5, 0
	s_cbranch_scc0 .Lip3_exit_b
; #define MFMA(a, b, c) __builtin_amdgcn_mfma_f32_32x32x16_bf16((a), (b), (c), 0, 0, 0)
; #define G_ISSUE(ks_, buf_) do { \
;     const bf16_t* wq_ = wp + (ks_) * wks; const bf16_t* xq_ = xp + (ks_) * xks; char* lb_ = ld + (buf_) * STAGE; \
;     dma16(wq_, lb_); dma16(wq_ + 2048, lb_ + 4096); \
;     _Pragma("unroll") for (int i_ = 0; i_ < TJ; ++i_) dma16(xq_ + i_ * 2048, lb_ + 8192 + i_ * 4096); } while (0)
; template <bool VMODE, int TJ>
; DI void gemm_mainloop(const bf16_t* __restrict__ W, const bf16_t* __restrict__ X, int NW, char* smem, f32x16 (&acc)[2][TJ]) {
;     ...
;         for (int ks = 0; ks < 32; ++ks) {
;             if (ks < 31) asm volatile("s_waitcnt vmcnt(6)" ::: "memory");
;             else asm volatile("s_waitcnt vmcnt(0)" ::: "memory");
;             __builtin_amdgcn_s_barrier();
;             const char* sw = smem + bc * STAGE + wf * 64 * 64;
;             const char* sx = smem + bc * STAGE + 8192 + wt * (32 * TJ) * 64;
;             bf16x8 fw[2], fx[TJ], gw[2], gx[TJ];
; #pragma unroll
;             for (int i = 0; i < 2; ++i) fw[i] = *(const bf16x8*)(sw + i * 32 * 64 + fo0);
; #pragma unroll
;             for (int j = 0; j < TJ; ++j) fx[j] = *(const bf16x8*)(sx + j * 32 * 64 + fo0);
;             __builtin_amdgcn_sched_barrier(0);
;             if (ks + 2 < 32) G_ISSUE(ks + 2, bn);
;             __builtin_amdgcn_sched_barrier(0);
; #pragma unroll
;             for (int i = 0; i < 2; ++i) gw[i] = *(const bf16x8*)(sw + i * 32 * 64 + fo1);
; #pragma unroll
;             for (int j = 0; j < TJ; ++j) gx[j] = *(const bf16x8*)(sx + j * 32 * 64 + fo1);
; #pragma unroll
;             for (int i = 0; i < 2; ++i)
; #pragma unroll
;                 for (int j = 0; j < TJ; ++j) acc[i][j] = VMODE ? MFMA(fx[j], fw[i], acc[i][j]) : MFMA(fw[i], fx[j], acc[i][j]);
; #pragma unroll
;             for (int i = 0; i < 2; ++i)
; #pragma unroll
;                 for (int j = 0; j < TJ; ++j) acc[i][j] = VMODE ? MFMA(gx[j], gw[i], acc[i][j]) : MFMA(gw[i], gx[j], acc[i][j]);
;             bc = (bc == 2) ? 0 : bc + 1; bn = (bn == 2) ? 0 : bn + 1;
;         }
;     }
;     ...
;     __syncthreads();
	s_waitcnt vmcnt(6)
	s_waitcnt lgkmcnt(0)
	s_barrier
	ds_read_b128 v[136:139], v238
	ds_read_b128 v[140:143], v238 offset:2048
	ds_read_b128 v[144:147], v239 offset:8192
	ds_read_b128 v[148:151], v239 offset:10240
	ds_read_b128 v[152:155], v239 offset:12288
	ds_read_b128 v[156:159], v239 offset:14336
	s_mul_i32 s7, s4, 0x6000
	s_add_i32 s101, s7, s100
	s_add_i32 s7, s6, 1
	s_cmp_lg_u32 s6, 2
	s_cselect_b32 s6, s7, 0
	s_add_i32 s7, s4, 1
	s_cmp_lg_u32 s4, 2
	s_cselect_b32 s4, s7, 0
	s_add_i32 s5, s5, -1
	s_add_u32 s56, s56, 0x120000
	s_addc_u32 s57, s57, 0
	s_add_u32 s52, s52, 0x38000
	s_addc_u32 s53, s53, 0
	s_mov_b32 m0, s101
	v_mfma_f32_32x32x16_bf16 v[112:127], v[160:163], v[164:167], v[112:127]
	global_load_lds_dwordx4 v170, s[52:53]
	s_add_u32 m0, s101, 0x1000
	v_mfma_f32_32x32x16_bf16 v[96:111], v[180:183], v[164:167], v[96:111]
	global_load_lds_dwordx4 v171, s[52:53]
	s_add_u32 m0, s101, 0x2000
	v_mfma_f32_32x32x16_bf16 v[80:95], v[184:187], v[164:167], v[80:95]
	global_load_lds_dwordx4 v172, s[56:57]
	s_add_u32 m0, s101, 0x3000
	v_mfma_f32_32x32x16_bf16 v[64:79], v[188:191], v[164:167], v[64:79]
	global_load_lds_dwordx4 v173, s[56:57]
	s_add_u32 m0, s101, 0x4000
	v_mfma_f32_32x32x16_bf16 v[48:63], v[160:163], v[176:179], v[48:63]
	global_load_lds_dwordx4 v174, s[56:57]
	s_add_u32 m0, s101, 0x5000
	v_mfma_f32_32x32x16_bf16 v[32:47], v[180:183], v[176:179], v[32:47]
	global_load_lds_dwordx4 v175, s[56:57]
	v_mfma_f32_32x32x16_bf16 v[16:31], v[184:187], v[176:179], v[16:31]
	v_mfma_f32_32x32x16_bf16 v[0:15], v[188:191], v[176:179], v[0:15]
	s_waitcnt lgkmcnt(0)
	v_mfma_f32_32x32x16_bf16 v[112:127], v[144:147], v[136:139], v[112:127]
	ds_read_b128 v[160:163], v241 offset:8192
	v_mfma_f32_32x32x16_bf16 v[96:111], v[148:151], v[136:139], v[96:111]
	ds_read_b128 v[164:167], v240
	v_mfma_f32_32x32x16_bf16 v[80:95], v[152:155], v[136:139], v[80:95]
	ds_read_b128 v[176:179], v240 offset:2048
	v_mfma_f32_32x32x16_bf16 v[64:79], v[156:159], v[136:139], v[64:79]
	ds_read_b128 v[180:183], v241 offset:10240
	v_mfma_f32_32x32x16_bf16 v[48:63], v[144:147], v[140:143], v[48:63]
	ds_read_b128 v[184:187], v241 offset:12288
	v_mfma_f32_32x32x16_bf16 v[32:47], v[148:151], v[140:143], v[32:47]
	ds_read_b128 v[188:191], v241 offset:14336
	v_mfma_f32_32x32x16_bf16 v[16:31], v[152:155], v[140:143], v[16:31]
	v_mfma_f32_32x32x16_bf16 v[0:15], v[156:159], v[140:143], v[0:15]
	s_cmp_lg_u32 s5, 0
	s_cbranch_scc1 .LBB0_289
.Lip3_exit_b:
	s_waitcnt lgkmcnt(0)
	v_mfma_f32_32x32x16_bf16 v[112:127], v[160:163], v[164:167], v[112:127]
	v_mfma_f32_32x32x16_bf16 v[96:111], v[180:183], v[164:167], v[96:111]
	v_mfma_f32_32x32x16_bf16 v[80:95], v[184:187], v[164:167], v[80:95]
	v_mfma_f32_32x32x16_bf16 v[64:79], v[188:191], v[164:167], v[64:79]
	v_mfma_f32_32x32x16_bf16 v[48:63], v[160:163], v[176:179], v[48:63]
	v_mfma_f32_32x32x16_bf16 v[32:47], v[180:183], v[176:179], v[32:47]
	v_mfma_f32_32x32x16_bf16 v[16:31], v[184:187], v[176:179], v[16:31]
	v_mfma_f32_32x32x16_bf16 v[0:15], v[188:191], v[176:179], v[0:15]
	v_add_u32_e32 v154, 32, v134
	v_add_u32_e32 v133, 32, v133
	v_add_u32_e32 v155, v154, v131
	v_add_u32_e32 v156, v133, v131
	s_waitcnt vmcnt(6)
	s_barrier
	ds_read_b128 v[134:137], v155
	ds_read_b128 v[138:141], v155 offset:2048
	ds_read_b128 v[128:131], v156 offset:8192
	ds_read_b128 v[142:145], v156 offset:10240
	ds_read_b128 v[146:149], v156 offset:12288
	ds_read_b128 v[150:153], v156 offset:14336
	v_add_u32_e32 v172, v133, v132
	s_waitcnt lgkmcnt(0)
	v_mfma_f32_32x32x16_bf16 v[112:127], v[128:131], v[134:137], v[112:127]
	v_add_u32_e32 v160, v154, v132
	v_mfma_f32_32x32x16_bf16 v[48:63], v[128:131], v[138:141], v[48:63]
	ds_read_b128 v[128:131], v172 offset:8192
	v_mfma_f32_32x32x16_bf16 v[96:111], v[142:145], v[134:137], v[96:111]
	v_mfma_f32_32x32x16_bf16 v[80:95], v[146:149], v[134:137], v[80:95]
	v_mfma_f32_32x32x16_bf16 v[64:79], v[150:153], v[134:137], v[64:79]
	v_mfma_f32_32x32x16_bf16 v[32:47], v[142:145], v[138:141], v[32:47]
	v_mfma_f32_32x32x16_bf16 v[16:31], v[146:149], v[138:141], v[16:31]
	v_mfma_f32_32x32x16_bf16 v[0:15], v[150:153], v[138:141], v[0:15]
	ds_read_b128 v[132:135], v160
	ds_read_b128 v[136:139], v160 offset:2048
	ds_read_b128 v[140:143], v172 offset:10240
	ds_read_b128 v[144:147], v172 offset:12288
	ds_read_b128 v[148:151], v172 offset:14336
	s_waitcnt vmcnt(0)
	s_barrier
	s_waitcnt lgkmcnt(0)
	v_mfma_f32_32x32x16_bf16 v[112:127], v[128:131], v[132:135], v[112:127]
	v_mfma_f32_32x32x16_bf16 v[96:111], v[140:143], v[132:135], v[96:111]
	v_mfma_f32_32x32x16_bf16 v[80:95], v[144:147], v[132:135], v[80:95]
	v_mfma_f32_32x32x16_bf16 v[64:79], v[148:151], v[132:135], v[64:79]
	v_mfma_f32_32x32x16_bf16 v[48:63], v[128:131], v[136:139], v[48:63]
	v_mfma_f32_32x32x16_bf16 v[32:47], v[140:143], v[136:139], v[32:47]
	v_mfma_f32_32x32x16_bf16 v[16:31], v[144:147], v[136:139], v[16:31]
	ds_read_b128 v[128:131], v155 offset:24576
	ds_read_b128 v[132:135], v155 offset:26624
	ds_read_b128 v[140:143], v156 offset:32768
	ds_read_b128 v[144:147], v156 offset:34816
	ds_read_b128 v[152:155], v156 offset:36864
	ds_read_b128 v[156:159], v156 offset:38912
	v_mfma_f32_32x32x16_bf16 v[0:15], v[148:151], v[136:139], v[0:15]
	s_waitcnt lgkmcnt(0)
	v_mfma_f32_32x32x16_bf16 v[112:127], v[140:143], v[128:131], v[112:127]
	ds_read_b128 v[136:139], v160 offset:24576
	ds_read_b128 v[148:151], v160 offset:26624
	ds_read_b128 v[160:163], v172 offset:32768
	ds_read_b128 v[164:167], v172 offset:34816
	ds_read_b128 v[168:171], v172 offset:36864
	ds_read_b128 v[172:175], v172 offset:38912
	s_waitcnt vmcnt(0) lgkmcnt(0)
	s_barrier
; DI unsigned pk2(float a, float b) { f2_t v = {a, b}; bf2_t r = __builtin_convertvector(v, bf2_t); return __builtin_bit_cast(unsigned, r); }
; DI int otid() { int t = threadIdx.x; asm volatile("" : "+v"(t)); return t; }
; template <int NIT>
; DI void stage_flush_bf16(const char* sb, bf16_t* gdst, int lane) {
; #pragma unroll
;     for (int it = 0; it < NIT; ++it) {
;         const int c = lane + 64 * it, row = c >> 3, lc = (c & 7) ^ (row & 7);
;         const u32x4_t v = *(const u32x4_t*)(sb + c * 16);
;         *(u32x4_t*)(gdst + row * 64 + lc * 8) = v;
;     }
; }
; DI void epi_v(const Params& p, int mtile, int vf0, f32x16 (&acc)[2][4], char* smem) {
;     const int tid = otid(), lane = tid & 63, wave = tid >> 6, r = lane & 31, h = lane >> 5, wf = wave & 1, wt = wave >> 1;
;     const int b = mtile / 9, t0 = (mtile % 9) * 256;
;     char* sb = smem + wave * 16384;
; #pragma unroll
;     for (int i = 0; i < 2; ++i)
; #pragma unroll
;         for (int j = 0; j < 4; ++j)
; #pragma unroll
;             for (int q = 0; q < 4; ++q) {
;                 uint2 o; o.x = pk2(acc[i][j][4 * q], acc[i][j][4 * q + 1]); o.y = pk2(acc[i][j][4 * q + 2], acc[i][j][4 * q + 3]);
;                 stage_quad_bf16(sb + (j >> 1) * 8192, 32 * i + r, 4 * (j & 1) + 2 * (q >> 1) + h, q & 1, o);
;             }
;     bf16_t* g0 = p.vT + (((size_t)b * 12 + (vf0 >> 6) + wf) * 36 + (t0 >> 6) + 2 * wt) * 4096;
;     stage_flush_bf16<8>(sb, g0, lane);
;     stage_flush_bf16<8>(sb + 8192, g0 + 4096, lane);
; }
	s_lshr_b32 s4, s47, 31
	s_ashr_i32 s5, s47, 1
	s_add_i32 s6, s5, s4
	v_mfma_f32_32x32x16_bf16 v[96:111], v[144:147], v[128:131], v[96:111]
	s_mul_i32 s4, s6, 9
	s_sub_i32 s8, s50, s4
	s_mul_hi_i32 s7, s6, 12
	s_mul_i32 s6, s6, 12
	s_lshr_b32 s9, s46, 6
	s_add_u32 s6, s6, s9
	s_addc_u32 s7, s7, 0
	v_mfma_f32_32x32x16_bf16 v[0:15], v[156:159], v[132:135], v[0:15]
	v_mfma_f32_32x32x16_bf16 v[112:127], v[160:163], v[136:139], v[112:127]
	v_mfma_f32_32x32x16_bf16 v[96:111], v[164:167], v[136:139], v[96:111]
	s_nop 10
	v_cvt_pk_bf16_f32 v112, v112, v113
	v_cvt_pk_bf16_f32 v113, v114, v115
	v_cvt_pk_bf16_f32 v115, v118, v119
	v_mfma_f32_32x32x16_bf16 v[32:47], v[144:147], v[132:135], v[32:47]
	v_cvt_pk_bf16_f32 v96, v96, v97
	v_cvt_pk_bf16_f32 v97, v98, v99
	v_cvt_pk_bf16_f32 v99, v102, v103
	v_mfma_f32_32x32x16_bf16 v[80:95], v[152:155], v[128:131], v[80:95]
	v_mfma_f32_32x32x16_bf16 v[64:79], v[156:159], v[128:131], v[64:79]
	v_mov_b32_e32 v128, v200
	s_load_dwordx2 s[4:5], s[0:1], 0xc8
	v_ashrrev_i32_e32 v130, 6, v128
	v_bfe_u32 v131, v128, 5, 1
	v_bitop3_b32 v114, v131, v128, 7 bitop3:0x78
	v_and_b32_e32 v192, 1, v130
	v_mfma_f32_32x32x16_bf16 v[0:15], v[172:175], v[148:151], v[0:15]
	v_and_b32_e32 v129, 63, v128
	v_mfma_f32_32x32x16_bf16 v[48:63], v[140:143], v[132:135], v[48:63]
	s_nop 9
	v_cvt_pk_bf16_f32 v0, v0, v1
	v_cvt_pk_bf16_f32 v1, v2, v3
	v_cvt_pk_bf16_f32 v2, v4, v5
	v_cvt_pk_bf16_f32 v3, v6, v7
	v_bfe_u32 v6, v128, 3, 3
	v_mfma_f32_32x32x16_bf16 v[16:31], v[152:155], v[132:135], v[16:31]
	v_lshlrev_b32_e32 v133, 7, v128
	v_lshl_add_u32 v132, v130, 14, 32
	v_and_b32_e32 v133, 0xf80, v133
	v_add_u32_e32 v133, v132, v133
	v_and_b32_e32 v134, 7, v128
	v_lshl_add_u32 v135, v114, 4, v133
	v_cvt_pk_bf16_f32 v114, v116, v117
	ds_write_b128 v135, v[112:115]
	v_bitop3_b32 v114, v131, v134, 2 bitop3:0x36
	v_cvt_pk_bf16_f32 v112, v120, v121
	v_cvt_pk_bf16_f32 v113, v122, v123
	v_lshl_add_u32 v116, v114, 4, v133
	v_cvt_pk_bf16_f32 v114, v124, v125
	v_cvt_pk_bf16_f32 v115, v126, v127
	v_bitop3_b32 v98, v131, v134, 4 bitop3:0x36
	v_mfma_f32_32x32x16_bf16 v[32:47], v[164:167], v[148:151], v[32:47]
	ds_write_b128 v116, v[112:115]
	v_lshl_add_u32 v112, v98, 4, v133
	v_cvt_pk_bf16_f32 v98, v100, v101
	ds_write_b128 v112, v[96:99]
	v_bitop3_b32 v98, v131, v134, 6 bitop3:0x36
	v_lshl_add_u32 v100, v98, 4, v133
	ds_write_b128 v112, v[0:3] offset:12288
	v_cvt_pk_bf16_f32 v0, v8, v9
	v_cvt_pk_bf16_f32 v1, v10, v11
	v_cvt_pk_bf16_f32 v2, v12, v13
	v_cvt_pk_bf16_f32 v3, v14, v15
	v_mfma_f32_32x32x16_bf16 v[16:31], v[168:171], v[148:151], v[16:31]
	ds_write_b128 v100, v[0:3] offset:12288
	v_and_b32_e32 v2, -2, v130
	v_lshl_add_u32 v2, s8, 2, v2
	v_lshl_add_u64 v[0:1], s[6:7], 0, v[192:193]
	v_ashrrev_i32_e32 v3, 31, v2
	v_mad_u64_u32 v[2:3], s[6:7], v0, 36, v[2:3]
	v_cvt_pk_bf16_f32 v96, v104, v105
	v_cvt_pk_bf16_f32 v97, v106, v107
	v_cvt_pk_bf16_f32 v98, v108, v109
	v_cvt_pk_bf16_f32 v99, v110, v111
	v_mad_i32_i24 v3, v1, 36, v3
	ds_write_b128 v100, v[96:99]
	v_cvt_pk_bf16_f32 v32, v32, v33
	v_cvt_pk_bf16_f32 v33, v34, v35
	v_cvt_pk_bf16_f32 v34, v36, v37
	v_lshlrev_b64 v[0:1], 13, v[2:3]
	v_lshl_add_u32 v37, v129, 4, v132
	s_waitcnt lgkmcnt(0)
	v_lshl_add_u64 v[4:5], s[4:5], 0, v[0:1]
	ds_read_b128 v[0:3], v37
	v_xor_b32_e32 v8, v6, v128
	v_cvt_pk_bf16_f32 v16, v16, v17
	v_cvt_pk_bf16_f32 v17, v18, v19
	v_cvt_pk_bf16_f32 v18, v20, v21
	v_cvt_pk_bf16_f32 v19, v22, v23
	v_lshlrev_b32_e32 v192, 7, v6
	v_lshlrev_b32_e32 v8, 4, v8
	ds_write_b128 v135, v[16:19] offset:12288
	v_cvt_pk_bf16_f32 v19, v30, v31
	v_lshl_add_u64 v[6:7], v[4:5], 0, v[192:193]
	v_and_b32_e32 v30, 0x70, v8
	v_mov_b32_e32 v31, v193
	v_lshl_add_u64 v[6:7], v[6:7], 0, v[30:31]
	v_cvt_pk_bf16_f32 v35, v38, v39
	s_waitcnt lgkmcnt(1)
	global_store_dwordx4 v[6:7], v[0:3], off
	ds_write_b128 v112, v[32:35] offset:4096
	v_cvt_pk_bf16_f32 v34, v44, v45
	v_or_b32_e32 v0, 64, v129
	v_lshl_add_u32 v44, v0, 4, v132
	v_lshrrev_b32_e32 v6, 3, v0
	ds_read_b128 v[0:3], v44
	v_xor_b32_e32 v8, v6, v128
	v_cvt_pk_bf16_f32 v17, v26, v27
	v_lshlrev_b32_e32 v26, 7, v6
	v_mov_b32_e32 v27, v193
	v_lshlrev_b32_e32 v8, 4, v8
	v_cvt_pk_bf16_f32 v18, v28, v29
	v_lshl_add_u64 v[6:7], v[4:5], 0, v[26:27]
	v_and_b32_e32 v28, 0x70, v8
	v_mov_b32_e32 v29, v193
	v_lshl_add_u64 v[6:7], v[6:7], 0, v[28:29]
	s_waitcnt lgkmcnt(0)
	global_store_dwordx4 v[6:7], v[0:3], off
	v_mov_b32_e32 v23, v193
	v_mfma_f32_32x32x16_bf16 v[48:63], v[160:163], v[148:151], v[48:63]
	v_or_b32_e32 v0, 0x80, v129
	v_lshl_add_u32 v45, v0, 4, v132
	v_lshrrev_b32_e32 v6, 3, v0
	ds_read_b128 v[0:3], v45
	v_xor_b32_e32 v8, v6, v128
	v_lshlrev_b32_e32 v22, 7, v6
	v_lshlrev_b32_e32 v8, 4, v8
	v_cvt_pk_bf16_f32 v16, v24, v25
	v_lshl_add_u64 v[6:7], v[4:5], 0, v[22:23]
	v_and_b32_e32 v24, 0x70, v8
	v_mov_b32_e32 v25, v193
	v_lshl_add_u64 v[6:7], v[6:7], 0, v[24:25]
	s_waitcnt lgkmcnt(0)
; template <int NIT>
; DI void stage_flush_bf16(const char* sb, bf16_t* gdst, int lane) {
; #pragma unroll
;     for (int it = 0; it < NIT; ++it) {
;         const int c = lane + 64 * it, row = c >> 3, lc = (c & 7) ^ (row & 7);
;         const u32x4_t v = *(const u32x4_t*)(sb + c * 16);
;         *(u32x4_t*)(gdst + row * 64 + lc * 8) = v;
;     }
; }
; DI void epi_v(const Params& p, int mtile, int vf0, f32x16 (&acc)[2][4], char* smem) {
;     ...
;     bf16_t* g0 = p.vT + (((size_t)b * 12 + (vf0 >> 6) + wf) * 36 + (t0 >> 6) + 2 * wt) * 4096;
;     stage_flush_bf16<8>(sb, g0, lane);
;     stage_flush_bf16<8>(sb + 8192, g0 + 4096, lane);
	global_store_dwordx4 v[6:7], v[0:3], off
	ds_write_b128 v116, v[16:19] offset:12288
	v_mov_b32_e32 v19, v193
	v_or_b32_e32 v0, 0xc0, v129
	v_lshl_add_u32 v36, v0, 4, v132
	v_lshrrev_b32_e32 v6, 3, v0
	ds_read_b128 v[0:3], v36
	v_xor_b32_e32 v8, v6, v128
	v_lshlrev_b32_e32 v18, 7, v6
	v_lshlrev_b32_e32 v8, 4, v8
	v_lshl_add_u64 v[6:7], v[4:5], 0, v[18:19]
	v_and_b32_e32 v20, 0x70, v8
	v_mov_b32_e32 v21, v193
	v_cvt_pk_bf16_f32 v48, v48, v49
	v_cvt_pk_bf16_f32 v49, v50, v51
	v_cvt_pk_bf16_f32 v50, v52, v53
	v_cvt_pk_bf16_f32 v51, v54, v55
	v_lshl_add_u64 v[6:7], v[6:7], 0, v[20:21]
	ds_write_b128 v135, v[48:51] offset:4096
	v_cvt_pk_bf16_f32 v48, v56, v57
	v_cvt_pk_bf16_f32 v49, v58, v59
	v_cvt_pk_bf16_f32 v50, v60, v61
	v_cvt_pk_bf16_f32 v51, v62, v63
	v_cvt_pk_bf16_f32 v32, v40, v41
	v_cvt_pk_bf16_f32 v33, v42, v43
	v_cvt_pk_bf16_f32 v35, v46, v47
	s_waitcnt lgkmcnt(1)
	global_store_dwordx4 v[6:7], v[0:3], off
	ds_write_b128 v116, v[48:51] offset:4096
	ds_write_b128 v100, v[32:35] offset:4096
	v_or_b32_e32 v0, 0x100, v129
	v_lshl_add_u32 v35, v0, 4, v132
	v_lshrrev_b32_e32 v6, 3, v0
	ds_read_b128 v[0:3], v35
	v_xor_b32_e32 v8, v6, v128
	v_lshlrev_b32_e32 v14, 7, v6
	v_mov_b32_e32 v15, v193
	v_lshlrev_b32_e32 v8, 4, v8
	v_lshl_add_u64 v[6:7], v[4:5], 0, v[14:15]
	v_and_b32_e32 v16, 0x70, v8
	v_mov_b32_e32 v17, v193
	v_lshl_add_u64 v[6:7], v[6:7], 0, v[16:17]
	s_waitcnt lgkmcnt(0)
	global_store_dwordx4 v[6:7], v[0:3], off
	v_mov_b32_e32 v11, v193
	v_mov_b32_e32 v13, v193
	v_or_b32_e32 v0, 0x140, v129
	v_lshl_add_u32 v34, v0, 4, v132
	v_lshrrev_b32_e32 v6, 3, v0
	ds_read_b128 v[0:3], v34
	v_xor_b32_e32 v8, v6, v128
	v_lshlrev_b32_e32 v10, 7, v6
	v_lshlrev_b32_e32 v8, 4, v8
	v_lshl_add_u64 v[6:7], v[4:5], 0, v[10:11]
	v_and_b32_e32 v12, 0x70, v8
	v_lshl_add_u64 v[6:7], v[6:7], 0, v[12:13]
	s_waitcnt lgkmcnt(0)
	global_store_dwordx4 v[6:7], v[0:3], off
	v_mfma_f32_32x32x16_bf16 v[80:95], v[168:171], v[136:139], v[80:95]
	v_mov_b32_e32 v7, v193
	v_or_b32_e32 v0, 0x180, v129
	v_lshl_add_u32 v33, v0, 4, v132
	v_lshrrev_b32_e32 v6, 3, v0
	ds_read_b128 v[0:3], v33
	v_xor_b32_e32 v8, v6, v128
	v_lshlrev_b32_e32 v6, 7, v6
	v_mfma_f32_32x32x16_bf16 v[64:79], v[172:175], v[136:139], v[64:79]
	v_lshlrev_b32_e32 v8, 4, v8
	v_lshl_add_u64 v[38:39], v[4:5], 0, v[6:7]
	v_and_b32_e32 v8, 0x70, v8
	v_mov_b32_e32 v9, v193
	v_lshl_add_u64 v[38:39], v[38:39], 0, v[8:9]
	s_waitcnt lgkmcnt(0)
	global_store_dwordx4 v[38:39], v[0:3], off
	v_cvt_pk_bf16_f32 v80, v80, v81
	v_cvt_pk_bf16_f32 v81, v82, v83
	v_or_b32_e32 v0, 0x1c0, v129
	v_lshl_add_u32 v32, v0, 4, v132
	v_lshrrev_b32_e32 v1, 3, v0
	ds_read_b128 v[38:41], v32
	v_xor_b32_e32 v2, v1, v128
	v_cvt_pk_bf16_f32 v82, v84, v85
	v_cvt_pk_bf16_f32 v83, v86, v87
	v_cvt_pk_bf16_f32 v64, v64, v65
	v_cvt_pk_bf16_f32 v65, v66, v67
	v_cvt_pk_bf16_f32 v66, v68, v69
	v_cvt_pk_bf16_f32 v67, v70, v71
	v_lshlrev_b32_e32 v0, 7, v1
	v_mov_b32_e32 v1, v193
	v_lshlrev_b32_e32 v2, 4, v2
	ds_write_b128 v135, v[80:83] offset:8192
	v_cvt_pk_bf16_f32 v80, v88, v89
	v_cvt_pk_bf16_f32 v81, v90, v91
	v_cvt_pk_bf16_f32 v82, v92, v93
	v_cvt_pk_bf16_f32 v83, v94, v95
	ds_write_b128 v112, v[64:67] offset:8192
	v_cvt_pk_bf16_f32 v64, v72, v73
	v_cvt_pk_bf16_f32 v65, v74, v75
	v_cvt_pk_bf16_f32 v66, v76, v77
	v_cvt_pk_bf16_f32 v67, v78, v79
	v_lshl_add_u64 v[42:43], v[4:5], 0, v[0:1]
	v_and_b32_e32 v2, 0x70, v2
	v_mov_b32_e32 v3, v193
	ds_write_b128 v116, v[80:83] offset:8192
	ds_write_b128 v100, v[64:67] offset:8192
	v_lshl_add_u64 v[42:43], v[42:43], 0, v[2:3]
	s_waitcnt lgkmcnt(4)
	global_store_dwordx4 v[42:43], v[38:41], off
	ds_read_b128 v[38:41], v37 offset:8192
	v_lshl_add_u64 v[4:5], v[4:5], 0, s[16:17]
	v_lshl_add_u64 v[42:43], v[4:5], 0, v[192:193]
	v_lshl_add_u64 v[30:31], v[42:43], 0, v[30:31]
	v_lshl_add_u64 v[26:27], v[4:5], 0, v[26:27]
	s_waitcnt lgkmcnt(0)
	global_store_dwordx4 v[30:31], v[38:41], off
	ds_read_b128 v[38:41], v44 offset:8192
	v_lshl_add_u64 v[26:27], v[26:27], 0, v[28:29]
	v_lshl_add_u64 v[22:23], v[4:5], 0, v[22:23]
	v_lshl_add_u64 v[22:23], v[22:23], 0, v[24:25]
	v_lshl_add_u64 v[18:19], v[4:5], 0, v[18:19]
	s_waitcnt lgkmcnt(0)
	global_store_dwordx4 v[26:27], v[38:41], off
	ds_read_b128 v[26:29], v45 offset:8192
	v_lshl_add_u64 v[18:19], v[18:19], 0, v[20:21]
	v_lshl_add_u64 v[14:15], v[4:5], 0, v[14:15]
	v_lshl_add_u64 v[14:15], v[14:15], 0, v[16:17]
	v_lshl_add_u64 v[10:11], v[4:5], 0, v[10:11]
	s_waitcnt lgkmcnt(0)
	global_store_dwordx4 v[22:23], v[26:29], off
	ds_read_b128 v[22:25], v36 offset:8192
	v_lshl_add_u64 v[10:11], v[10:11], 0, v[12:13]
	v_lshl_add_u64 v[6:7], v[4:5], 0, v[6:7]
	v_lshl_add_u64 v[6:7], v[6:7], 0, v[8:9]
	v_lshl_add_u64 v[0:1], v[4:5], 0, v[0:1]
	s_waitcnt lgkmcnt(0)
	global_store_dwordx4 v[18:19], v[22:25], off
	ds_read_b128 v[18:21], v35 offset:8192
	v_lshl_add_u64 v[0:1], v[0:1], 0, v[2:3]
	s_waitcnt lgkmcnt(0)
	global_store_dwordx4 v[14:15], v[18:21], off
	ds_read_b128 v[14:17], v34 offset:8192
	s_waitcnt lgkmcnt(0)
	global_store_dwordx4 v[10:11], v[14:17], off
	ds_read_b128 v[10:13], v33 offset:8192
	s_waitcnt lgkmcnt(0)
	global_store_dwordx4 v[6:7], v[10:13], off
	ds_read_b128 v[6:9], v32 offset:8192
	s_waitcnt lgkmcnt(0)
	global_store_dwordx4 v[0:1], v[6:9], off
	s_branch .LBB0_185
